# v058 + packed f32 VALU ops (v_pk_mul/fma_f32) in the QKV and Up GEMM epilogues split into single-lane ops (bit-identical)
# speedup vs baseline: 1.0030x; 1.0030x over previous
; __device__ __forceinline__ unsigned pkbf(float lo, float hi) { f32x2_t v = {lo, hi}; bf16x2_t b = __builtin_convertvector(v, bf16x2_t); return __builtin_bit_cast(unsigned, b); }
;     __device__ __forceinline__ void operator()(const f32x4 (&acc)[2][2][4][2], const pg8::Unit& u, int wr, int wc, int fr, int fq) const {
;         const int pn = u.pn; const int kind = pn < 4 ? 0 : (pn < 4 + nk_tiles ? 1 : 2);
;         const int hd = (kind == 0 ? pn : (kind == 1 ? pn - 4 : pn - 4 - nk_tiles)) * 4 + wc;
;         bf16_t* dst = Q + (size_t)kind * kstride + hd * 64 + 8 * fq; const int pitch = kind == 0 ? DM : kvpitch;
;         const float* gp = gains + (kind & 1) * 64 + 8 * fq;
;         const bool dorope = (rope != nullptr) && kind < 2 && u.pm < 128;
;         const float* rp = rope + 8 * (fq & 1);
;         int rbase = u.pm * 256 + wr * 64 + fr; asm volatile("" : "+v"(rbase));
;         const int paddr = ((fr + 16 * fq) ^ 32) << 2;
; #pragma unroll
;         for (int ai = 0; ai < 2; ++ai)
; #pragma unroll
;             for (int m = 0; m < 4; ++m) {
;                 const int row = rbase + ai * 128 + m * 16;
;                 float rs = 1.0f;
;                 if (kind < 2) {
;                     float ss = 0.f;
; #pragma unroll
;                     for (int bj = 0; bj < 2; ++bj)
; #pragma unroll
;                         for (int n = 0; n < 2; ++n) { const f32x4 x = acc[ai][bj][m][n]; ss += (x[0] * x[0] + x[1] * x[1]) + (x[2] * x[2] + x[3] * x[3]); }
;                     ss = xsum4(ss);
;                     rs = rsqrtf(ss * (1.0f / 64.0f) + EPS);
;                 }
;                 const int t = row & (SEQ - 1);
; #pragma unroll
;                 for (int bj = 0; bj < 2; ++bj) {
;                     f32x4 v0 = acc[ai][bj][m][0], v1 = acc[ai][bj][m][1];
;                     if (kind < 2) {
;                         v0 = v0 * rs * *(const f32x4*)(gp + 32 * bj); v1 = v1 * rs * *(const f32x4*)(gp + 32 * bj + 4);
;     ...
;                     u32x4 w; w.x = pkbf(v0[0], v0[1]); w.y = pkbf(v0[2], v0[3]); w.z = pkbf(v1[0], v1[1]); w.w = pkbf(v1[2], v1[3]);
;                     *(u32x4*)(dst + (size_t)row * pitch + 32 * bj) = w;
.LBB0_220:
	s_sub_i32 s10, s28, s62
	s_add_i32 s11, s28, -4
	s_cmp_lt_i32 s28, s62
	s_cselect_b32 s10, s11, s10
	s_cselect_b32 s11, 1, 2
	s_cselect_b64 s[34:35], -1, 0
	s_cmp_lt_i32 s28, 4
	s_cselect_b32 s10, s28, s10
	s_cselect_b32 s11, 0, s11
	s_cselect_b64 s[30:31], -1, 0
	v_readlane_b32 s36, v241, 37
	v_readlane_b32 s37, v241, 38
	v_readlane_b32 s38, v240, 36
	v_readlane_b32 s39, v240, 38
	s_mul_i32 s13, s11, 0x4200000
	s_lshl_b32 s10, s10, 8
	s_or_b32 s10, s10, s57
	s_lshl_b32 s10, s10, 1
	s_add_u32 s36, s36, s13
	s_addc_u32 s37, s37, 0
	s_add_u32 s36, s36, s10
	s_addc_u32 s37, s37, 0
	s_cmp_lg_u32 s38, 0
	s_cselect_b32 s13, 11, 9
	s_cmp_lt_i32 s28, 4
	s_cselect_b32 s13, 11, s13
	s_cmp_eq_u32 s11, 1
	s_cselect_b32 s82, 0x100, 0
	s_cmp_lt_i32 s12, 0x80
	s_cselect_b32 s38, s39, 0
	s_cmp_lt_i32 s11, 2
	s_cselect_b32 s38, s38, 0
	s_cmp_eq_u32 s11, 2
	s_cbranch_scc1 .Lqkv_v
	s_cmp_lg_u32 s38, 0
	s_cbranch_scc1 .Lqkv_rope
	v_lshl_add_u64 v[214:215], v[136:137], 0, s[82:83]
	global_load_dwordx4 v[162:165], v[214:215], off
	global_load_dwordx4 v[166:169], v[214:215], off offset:16
	global_load_dwordx4 v[170:173], v[214:215], off offset:128
	global_load_dwordx4 v[174:177], v[214:215], off offset:144
	v_mul_f32_e32 v143, v125, v125
	v_mul_f32_e32 v144, v127, v127
	v_fmac_f32_e32 v143, v124, v124
	v_fmac_f32_e32 v144, v126, v126
	v_add_f32_e32 v142, v143, v144
	v_mul_f32_e32 v143, v121, v121
	v_mul_f32_e32 v144, v123, v123
	v_fmac_f32_e32 v143, v120, v120
	v_fmac_f32_e32 v144, v122, v122
	v_add_f32_e32 v143, v143, v144
	v_add_f32_e32 v142, v142, v143
	v_mul_f32_e32 v143, v117, v117
	v_mul_f32_e32 v144, v119, v119
	v_fmac_f32_e32 v143, v116, v116
	v_fmac_f32_e32 v144, v118, v118
	v_add_f32_e32 v143, v143, v144
	v_add_f32_e32 v142, v142, v143
	v_mul_f32_e32 v143, v113, v113
	v_mul_f32_e32 v144, v115, v115
	v_fmac_f32_e32 v143, v112, v112
	v_fmac_f32_e32 v144, v114, v114
	v_add_f32_e32 v143, v143, v144
	v_add_f32_e32 v142, v142, v143
	v_mov_b32_e32 v143, v142
	s_nop 1
	v_permlane16_swap_b32_e32 v142, v143
	v_add_f32_e32 v142, v142, v143
	v_mov_b32_e32 v143, v142
	s_nop 1
	v_permlane32_swap_b32_e32 v142, v143
	v_add_f32_e32 v142, v142, v143
	v_fmamk_f32 v144, v142, 0x3c800000, v153
	v_rsq_f32_e32 v144, v144
	s_nop 0
	s_waitcnt vmcnt(0)
	v_mul_f32_e32 v124, v124, v144
	v_mul_f32_e32 v125, v125, v144
	v_mul_f32_e32 v126, v126, v144
	v_mul_f32_e32 v127, v127, v144
	v_mul_f32_e32 v124, v124, v162
	v_mul_f32_e32 v125, v125, v163
	v_mul_f32_e32 v126, v126, v164
	v_mul_f32_e32 v127, v127, v165
	v_mul_f32_e32 v120, v120, v144
	v_mul_f32_e32 v121, v121, v144
	v_mul_f32_e32 v122, v122, v144
	v_mul_f32_e32 v123, v123, v144
	v_mul_f32_e32 v120, v120, v166
	v_mul_f32_e32 v121, v121, v167
	v_mul_f32_e32 v122, v122, v168
	v_mul_f32_e32 v123, v123, v169
	v_mul_f32_e32 v116, v116, v144
	v_mul_f32_e32 v117, v117, v144
	v_mul_f32_e32 v118, v118, v144
	v_mul_f32_e32 v119, v119, v144
	v_mul_f32_e32 v116, v116, v170
	v_mul_f32_e32 v117, v117, v171
	v_mul_f32_e32 v118, v118, v172
	v_mul_f32_e32 v119, v119, v173
	v_mul_f32_e32 v112, v112, v144
	v_mul_f32_e32 v113, v113, v144
	v_mul_f32_e32 v114, v114, v144
	v_mul_f32_e32 v115, v115, v144
	v_mul_f32_e32 v112, v112, v174
	v_mul_f32_e32 v113, v113, v175
	v_mul_f32_e32 v114, v114, v176
	v_mul_f32_e32 v115, v115, v177
	v_lshl_add_u32 v142, s12, 8, v158
	v_lshl_add_u32 v142, v142, s13, v154
	v_cvt_pk_bf16_f32 v124, v124, v125
	v_cvt_pk_bf16_f32 v125, v126, v127
	v_cvt_pk_bf16_f32 v126, v120, v121
	v_cvt_pk_bf16_f32 v127, v122, v123
	global_store_dwordx4 v142, v[124:127], s[36:37]
	v_cvt_pk_bf16_f32 v116, v116, v117
	v_cvt_pk_bf16_f32 v117, v118, v119
	v_cvt_pk_bf16_f32 v118, v112, v113
	v_cvt_pk_bf16_f32 v119, v114, v115
	global_store_dwordx4 v142, v[116:119], s[36:37] offset:64
	v_mul_f32_e32 v143, v109, v109
	v_mul_f32_e32 v144, v111, v111
	v_fmac_f32_e32 v143, v108, v108
	v_fmac_f32_e32 v144, v110, v110
	v_add_f32_e32 v142, v143, v144
	v_mul_f32_e32 v143, v105, v105
	v_mul_f32_e32 v144, v107, v107
	v_fmac_f32_e32 v143, v104, v104
	v_fmac_f32_e32 v144, v106, v106
	v_add_f32_e32 v143, v143, v144
	v_add_f32_e32 v142, v142, v143
	v_mul_f32_e32 v143, v101, v101
	v_mul_f32_e32 v144, v103, v103
	v_fmac_f32_e32 v143, v100, v100
	v_fmac_f32_e32 v144, v102, v102
	v_add_f32_e32 v143, v143, v144
	v_add_f32_e32 v142, v142, v143
	v_mul_f32_e32 v143, v97, v97
	v_mul_f32_e32 v144, v99, v99
	v_fmac_f32_e32 v143, v96, v96
	v_fmac_f32_e32 v144, v98, v98
	v_add_f32_e32 v143, v143, v144
	v_add_f32_e32 v142, v142, v143
	v_mov_b32_e32 v143, v142
	s_nop 1
	v_permlane16_swap_b32_e32 v142, v143
	v_add_f32_e32 v142, v142, v143
	v_mov_b32_e32 v143, v142
	s_nop 1
	v_permlane32_swap_b32_e32 v142, v143
	v_add_f32_e32 v142, v142, v143
	v_fmamk_f32 v144, v142, 0x3c800000, v153
	v_rsq_f32_e32 v144, v144
	s_nop 0
	v_mul_f32_e32 v108, v108, v144
	v_mul_f32_e32 v109, v109, v144
	v_mul_f32_e32 v110, v110, v144
	v_mul_f32_e32 v111, v111, v144
	v_mul_f32_e32 v108, v108, v162
	v_mul_f32_e32 v109, v109, v163
	v_mul_f32_e32 v110, v110, v164
	v_mul_f32_e32 v111, v111, v165
	v_mul_f32_e32 v104, v104, v144
	v_mul_f32_e32 v105, v105, v144
	v_mul_f32_e32 v106, v106, v144
	v_mul_f32_e32 v107, v107, v144
	v_mul_f32_e32 v104, v104, v166
	v_mul_f32_e32 v105, v105, v167
	v_mul_f32_e32 v106, v106, v168
	v_mul_f32_e32 v107, v107, v169
	v_mul_f32_e32 v100, v100, v144
	v_mul_f32_e32 v101, v101, v144
	v_mul_f32_e32 v102, v102, v144
	v_mul_f32_e32 v103, v103, v144
	v_mul_f32_e32 v100, v100, v170
	v_mul_f32_e32 v101, v101, v171
	v_mul_f32_e32 v102, v102, v172
	v_mul_f32_e32 v103, v103, v173
	v_mul_f32_e32 v96, v96, v144
	v_mul_f32_e32 v97, v97, v144
	v_mul_f32_e32 v98, v98, v144
; __device__ __forceinline__ unsigned pkbf(float lo, float hi) { f32x2_t v = {lo, hi}; bf16x2_t b = __builtin_convertvector(v, bf16x2_t); return __builtin_bit_cast(unsigned, b); }
;     __device__ __forceinline__ void operator()(const f32x4 (&acc)[2][2][4][2], const pg8::Unit& u, int wr, int wc, int fr, int fq) const {
;     ...
;                 const int row = rbase + ai * 128 + m * 16;
;                 float rs = 1.0f;
;                 if (kind < 2) {
;                     float ss = 0.f;
; #pragma unroll
;                     for (int bj = 0; bj < 2; ++bj)
; #pragma unroll
;                         for (int n = 0; n < 2; ++n) { const f32x4 x = acc[ai][bj][m][n]; ss += (x[0] * x[0] + x[1] * x[1]) + (x[2] * x[2] + x[3] * x[3]); }
;                     ss = xsum4(ss);
;                     rs = rsqrtf(ss * (1.0f / 64.0f) + EPS);
;                 }
;                 const int t = row & (SEQ - 1);
; #pragma unroll
;                 for (int bj = 0; bj < 2; ++bj) {
;                     f32x4 v0 = acc[ai][bj][m][0], v1 = acc[ai][bj][m][1];
;                     if (kind < 2) {
;                         v0 = v0 * rs * *(const f32x4*)(gp + 32 * bj); v1 = v1 * rs * *(const f32x4*)(gp + 32 * bj + 4);
;                         if (dorope) {
;                             const int pos = bj ? (t & 63) : (t >> 6);
;                             const f32x4 c0 = *(const f32x4*)(rp + pos * 16), c1 = *(const f32x4*)(rp + pos * 16 + 4);
;                             const f32x4 s0 = *(const f32x4*)(rp + 2048 + pos * 16), s1 = *(const f32x4*)(rp + 2048 + pos * 16 + 4);
;                             f32x4 o0, o1;
; #pragma unroll
;                             for (int i = 0; i < 4; ++i) { const float p0 = __uint_as_float((unsigned)__builtin_amdgcn_ds_bpermute(paddr, (int)__float_as_uint(v0[i]))) * s0[i], p1 = __uint_as_float((unsigned)__builtin_amdgcn_ds_bpermute(paddr, (int)__float_as_uint(v1[i]))) * s1[i];
;                                 o0[i] = v0[i] * c0[i] + (fq >= 2 ? p0 : -p0); o1[i] = v1[i] * c1[i] + (fq >= 2 ? p1 : -p1); }
;                             v0 = o0; v1 = o1;
;                         }
;                     }
;                     u32x4 w; w.x = pkbf(v0[0], v0[1]); w.y = pkbf(v0[2], v0[3]); w.z = pkbf(v1[0], v1[1]); w.w = pkbf(v1[2], v1[3]);
;                     *(u32x4*)(dst + (size_t)row * pitch + 32 * bj) = w;
	v_mul_f32_e32 v99, v99, v144
	v_mul_f32_e32 v96, v96, v174
	v_mul_f32_e32 v97, v97, v175
	v_mul_f32_e32 v98, v98, v176
	v_mul_f32_e32 v99, v99, v177
	v_lshl_add_u32 v142, s12, 8, v158
	v_add_u32_e32 v142, 16, v142
	v_lshl_add_u32 v142, v142, s13, v154
	v_cvt_pk_bf16_f32 v108, v108, v109
	v_cvt_pk_bf16_f32 v109, v110, v111
	v_cvt_pk_bf16_f32 v110, v104, v105
	v_cvt_pk_bf16_f32 v111, v106, v107
	global_store_dwordx4 v142, v[108:111], s[36:37]
	v_cvt_pk_bf16_f32 v100, v100, v101
	v_cvt_pk_bf16_f32 v101, v102, v103
	v_cvt_pk_bf16_f32 v102, v96, v97
	v_cvt_pk_bf16_f32 v103, v98, v99
	global_store_dwordx4 v142, v[100:103], s[36:37] offset:64
	v_mul_f32_e32 v143, v93, v93
	v_mul_f32_e32 v144, v95, v95
	v_fmac_f32_e32 v143, v92, v92
	v_fmac_f32_e32 v144, v94, v94
	v_add_f32_e32 v142, v143, v144
	v_mul_f32_e32 v143, v89, v89
	v_mul_f32_e32 v144, v91, v91
	v_fmac_f32_e32 v143, v88, v88
	v_fmac_f32_e32 v144, v90, v90
	v_add_f32_e32 v143, v143, v144
	v_add_f32_e32 v142, v142, v143
	v_mul_f32_e32 v143, v85, v85
	v_mul_f32_e32 v144, v87, v87
	v_fmac_f32_e32 v143, v84, v84
	v_fmac_f32_e32 v144, v86, v86
	v_add_f32_e32 v143, v143, v144
	v_add_f32_e32 v142, v142, v143
	v_mul_f32_e32 v143, v81, v81
	v_mul_f32_e32 v144, v83, v83
	v_fmac_f32_e32 v143, v80, v80
	v_fmac_f32_e32 v144, v82, v82
	v_add_f32_e32 v143, v143, v144
	v_add_f32_e32 v142, v142, v143
	v_mov_b32_e32 v143, v142
	s_nop 1
	v_permlane16_swap_b32_e32 v142, v143
	v_add_f32_e32 v142, v142, v143
	v_mov_b32_e32 v143, v142
	s_nop 1
	v_permlane32_swap_b32_e32 v142, v143
	v_add_f32_e32 v142, v142, v143
	v_fmamk_f32 v144, v142, 0x3c800000, v153
	v_rsq_f32_e32 v144, v144
	s_nop 0
	v_mul_f32_e32 v92, v92, v144
	v_mul_f32_e32 v93, v93, v144
	v_mul_f32_e32 v94, v94, v144
	v_mul_f32_e32 v95, v95, v144
	v_mul_f32_e32 v92, v92, v162
	v_mul_f32_e32 v93, v93, v163
	v_mul_f32_e32 v94, v94, v164
	v_mul_f32_e32 v95, v95, v165
	v_mul_f32_e32 v88, v88, v144
	v_mul_f32_e32 v89, v89, v144
	v_mul_f32_e32 v90, v90, v144
	v_mul_f32_e32 v91, v91, v144
	v_mul_f32_e32 v88, v88, v166
	v_mul_f32_e32 v89, v89, v167
	v_mul_f32_e32 v90, v90, v168
	v_mul_f32_e32 v91, v91, v169
	v_mul_f32_e32 v84, v84, v144
	v_mul_f32_e32 v85, v85, v144
	v_mul_f32_e32 v86, v86, v144
	v_mul_f32_e32 v87, v87, v144
	v_mul_f32_e32 v84, v84, v170
	v_mul_f32_e32 v85, v85, v171
	v_mul_f32_e32 v86, v86, v172
	v_mul_f32_e32 v87, v87, v173
	v_mul_f32_e32 v80, v80, v144
	v_mul_f32_e32 v81, v81, v144
	v_mul_f32_e32 v82, v82, v144
	v_mul_f32_e32 v83, v83, v144
	v_mul_f32_e32 v80, v80, v174
	v_mul_f32_e32 v81, v81, v175
	v_mul_f32_e32 v82, v82, v176
	v_mul_f32_e32 v83, v83, v177
	v_lshl_add_u32 v142, s12, 8, v158
	v_add_u32_e32 v142, 32, v142
	v_lshl_add_u32 v142, v142, s13, v154
	v_cvt_pk_bf16_f32 v92, v92, v93
	v_cvt_pk_bf16_f32 v93, v94, v95
	v_cvt_pk_bf16_f32 v94, v88, v89
	v_cvt_pk_bf16_f32 v95, v90, v91
	global_store_dwordx4 v142, v[92:95], s[36:37]
	v_cvt_pk_bf16_f32 v84, v84, v85
	v_cvt_pk_bf16_f32 v85, v86, v87
	v_cvt_pk_bf16_f32 v86, v80, v81
	v_cvt_pk_bf16_f32 v87, v82, v83
	global_store_dwordx4 v142, v[84:87], s[36:37] offset:64
	v_mul_f32_e32 v143, v77, v77
	v_mul_f32_e32 v144, v79, v79
	v_fmac_f32_e32 v143, v76, v76
	v_fmac_f32_e32 v144, v78, v78
	v_add_f32_e32 v142, v143, v144
	v_mul_f32_e32 v143, v73, v73
	v_mul_f32_e32 v144, v75, v75
	v_fmac_f32_e32 v143, v72, v72
	v_fmac_f32_e32 v144, v74, v74
	v_add_f32_e32 v143, v143, v144
	v_add_f32_e32 v142, v142, v143
	v_mul_f32_e32 v143, v69, v69
	v_mul_f32_e32 v144, v71, v71
	v_fmac_f32_e32 v143, v68, v68
	v_fmac_f32_e32 v144, v70, v70
	v_add_f32_e32 v143, v143, v144
	v_add_f32_e32 v142, v142, v143
	v_mul_f32_e32 v143, v65, v65
	v_mul_f32_e32 v144, v67, v67
	v_fmac_f32_e32 v143, v64, v64
	v_fmac_f32_e32 v144, v66, v66
	v_add_f32_e32 v143, v143, v144
	v_add_f32_e32 v142, v142, v143
	v_mov_b32_e32 v143, v142
	s_nop 1
	v_permlane16_swap_b32_e32 v142, v143
	v_add_f32_e32 v142, v142, v143
	v_mov_b32_e32 v143, v142
	s_nop 1
	v_permlane32_swap_b32_e32 v142, v143
	v_add_f32_e32 v142, v142, v143
	v_fmamk_f32 v144, v142, 0x3c800000, v153
	v_rsq_f32_e32 v144, v144
	s_nop 0
	v_mul_f32_e32 v76, v76, v144
	v_mul_f32_e32 v77, v77, v144
	v_mul_f32_e32 v78, v78, v144
	v_mul_f32_e32 v79, v79, v144
	v_mul_f32_e32 v76, v76, v162
	v_mul_f32_e32 v77, v77, v163
	v_mul_f32_e32 v78, v78, v164
	v_mul_f32_e32 v79, v79, v165
	v_mul_f32_e32 v72, v72, v144
	v_mul_f32_e32 v73, v73, v144
	v_mul_f32_e32 v74, v74, v144
	v_mul_f32_e32 v75, v75, v144
	v_mul_f32_e32 v72, v72, v166
	v_mul_f32_e32 v73, v73, v167
	v_mul_f32_e32 v74, v74, v168
	v_mul_f32_e32 v75, v75, v169
	v_mul_f32_e32 v68, v68, v144
	v_mul_f32_e32 v69, v69, v144
	v_mul_f32_e32 v70, v70, v144
	v_mul_f32_e32 v71, v71, v144
	v_mul_f32_e32 v68, v68, v170
	v_mul_f32_e32 v69, v69, v171
	v_mul_f32_e32 v70, v70, v172
	v_mul_f32_e32 v71, v71, v173
	v_mul_f32_e32 v64, v64, v144
	v_mul_f32_e32 v65, v65, v144
	v_mul_f32_e32 v66, v66, v144
	v_mul_f32_e32 v67, v67, v144
	v_mul_f32_e32 v64, v64, v174
	v_mul_f32_e32 v65, v65, v175
	v_mul_f32_e32 v66, v66, v176
	v_mul_f32_e32 v67, v67, v177
	v_lshl_add_u32 v142, s12, 8, v158
	v_add_u32_e32 v142, 48, v142
	v_lshl_add_u32 v142, v142, s13, v154
	v_cvt_pk_bf16_f32 v76, v76, v77
	v_cvt_pk_bf16_f32 v77, v78, v79
	v_cvt_pk_bf16_f32 v78, v72, v73
	v_cvt_pk_bf16_f32 v79, v74, v75
	global_store_dwordx4 v142, v[76:79], s[36:37]
	v_cvt_pk_bf16_f32 v68, v68, v69
	v_cvt_pk_bf16_f32 v69, v70, v71
	v_cvt_pk_bf16_f32 v70, v64, v65
	v_cvt_pk_bf16_f32 v71, v66, v67
	global_store_dwordx4 v142, v[68:71], s[36:37] offset:64
	v_mul_f32_e32 v143, v61, v61
	v_mul_f32_e32 v144, v63, v63
	v_fmac_f32_e32 v143, v60, v60
	v_fmac_f32_e32 v144, v62, v62
; __device__ __forceinline__ unsigned pkbf(float lo, float hi) { f32x2_t v = {lo, hi}; bf16x2_t b = __builtin_convertvector(v, bf16x2_t); return __builtin_bit_cast(unsigned, b); }
;     __device__ __forceinline__ void operator()(const f32x4 (&acc)[2][2][4][2], const pg8::Unit& u, int wr, int wc, int fr, int fq) const {
;     ...
;                 const int row = rbase + ai * 128 + m * 16;
;                 float rs = 1.0f;
;                 if (kind < 2) {
;                     float ss = 0.f;
; #pragma unroll
;                     for (int bj = 0; bj < 2; ++bj)
; #pragma unroll
;                         for (int n = 0; n < 2; ++n) { const f32x4 x = acc[ai][bj][m][n]; ss += (x[0] * x[0] + x[1] * x[1]) + (x[2] * x[2] + x[3] * x[3]); }
;                     ss = xsum4(ss);
;                     rs = rsqrtf(ss * (1.0f / 64.0f) + EPS);
;                 }
;                 const int t = row & (SEQ - 1);
; #pragma unroll
;                 for (int bj = 0; bj < 2; ++bj) {
;                     f32x4 v0 = acc[ai][bj][m][0], v1 = acc[ai][bj][m][1];
;                     if (kind < 2) {
;                         v0 = v0 * rs * *(const f32x4*)(gp + 32 * bj); v1 = v1 * rs * *(const f32x4*)(gp + 32 * bj + 4);
;                         if (dorope) {
;                             const int pos = bj ? (t & 63) : (t >> 6);
;                             const f32x4 c0 = *(const f32x4*)(rp + pos * 16), c1 = *(const f32x4*)(rp + pos * 16 + 4);
;                             const f32x4 s0 = *(const f32x4*)(rp + 2048 + pos * 16), s1 = *(const f32x4*)(rp + 2048 + pos * 16 + 4);
;                             f32x4 o0, o1;
; #pragma unroll
;                             for (int i = 0; i < 4; ++i) { const float p0 = __uint_as_float((unsigned)__builtin_amdgcn_ds_bpermute(paddr, (int)__float_as_uint(v0[i]))) * s0[i], p1 = __uint_as_float((unsigned)__builtin_amdgcn_ds_bpermute(paddr, (int)__float_as_uint(v1[i]))) * s1[i];
;                                 o0[i] = v0[i] * c0[i] + (fq >= 2 ? p0 : -p0); o1[i] = v1[i] * c1[i] + (fq >= 2 ? p1 : -p1); }
;                             v0 = o0; v1 = o1;
;                         }
;                     }
;                     u32x4 w; w.x = pkbf(v0[0], v0[1]); w.y = pkbf(v0[2], v0[3]); w.z = pkbf(v1[0], v1[1]); w.w = pkbf(v1[2], v1[3]);
;                     *(u32x4*)(dst + (size_t)row * pitch + 32 * bj) = w;
	v_add_f32_e32 v142, v143, v144
	v_mul_f32_e32 v143, v57, v57
	v_mul_f32_e32 v144, v59, v59
	v_fmac_f32_e32 v143, v56, v56
	v_fmac_f32_e32 v144, v58, v58
	v_add_f32_e32 v143, v143, v144
	v_add_f32_e32 v142, v142, v143
	v_mul_f32_e32 v143, v53, v53
	v_mul_f32_e32 v144, v55, v55
	v_fmac_f32_e32 v143, v52, v52
	v_fmac_f32_e32 v144, v54, v54
	v_add_f32_e32 v143, v143, v144
	v_add_f32_e32 v142, v142, v143
	v_mul_f32_e32 v143, v49, v49
	v_mul_f32_e32 v144, v51, v51
	v_fmac_f32_e32 v143, v48, v48
	v_fmac_f32_e32 v144, v50, v50
	v_add_f32_e32 v143, v143, v144
	v_add_f32_e32 v142, v142, v143
	v_mov_b32_e32 v143, v142
	s_nop 1
	v_permlane16_swap_b32_e32 v142, v143
	v_add_f32_e32 v142, v142, v143
	v_mov_b32_e32 v143, v142
	s_nop 1
	v_permlane32_swap_b32_e32 v142, v143
	v_add_f32_e32 v142, v142, v143
	v_fmamk_f32 v144, v142, 0x3c800000, v153
	v_rsq_f32_e32 v144, v144
	s_nop 0
	v_mul_f32_e32 v60, v60, v144
	v_mul_f32_e32 v61, v61, v144
	v_mul_f32_e32 v62, v62, v144
	v_mul_f32_e32 v63, v63, v144
	v_mul_f32_e32 v60, v60, v162
	v_mul_f32_e32 v61, v61, v163
	v_mul_f32_e32 v62, v62, v164
	v_mul_f32_e32 v63, v63, v165
	v_mul_f32_e32 v56, v56, v144
	v_mul_f32_e32 v57, v57, v144
	v_mul_f32_e32 v58, v58, v144
	v_mul_f32_e32 v59, v59, v144
	v_mul_f32_e32 v56, v56, v166
	v_mul_f32_e32 v57, v57, v167
	v_mul_f32_e32 v58, v58, v168
	v_mul_f32_e32 v59, v59, v169
	v_mul_f32_e32 v52, v52, v144
	v_mul_f32_e32 v53, v53, v144
	v_mul_f32_e32 v54, v54, v144
	v_mul_f32_e32 v55, v55, v144
	v_mul_f32_e32 v52, v52, v170
	v_mul_f32_e32 v53, v53, v171
	v_mul_f32_e32 v54, v54, v172
	v_mul_f32_e32 v55, v55, v173
	v_mul_f32_e32 v48, v48, v144
	v_mul_f32_e32 v49, v49, v144
	v_mul_f32_e32 v50, v50, v144
	v_mul_f32_e32 v51, v51, v144
	v_mul_f32_e32 v48, v48, v174
	v_mul_f32_e32 v49, v49, v175
	v_mul_f32_e32 v50, v50, v176
	v_mul_f32_e32 v51, v51, v177
	v_lshl_add_u32 v142, s12, 8, v158
	v_add_u32_e32 v142, 128, v142
	v_lshl_add_u32 v142, v142, s13, v154
	v_cvt_pk_bf16_f32 v60, v60, v61
	v_cvt_pk_bf16_f32 v61, v62, v63
	v_cvt_pk_bf16_f32 v62, v56, v57
	v_cvt_pk_bf16_f32 v63, v58, v59
	global_store_dwordx4 v142, v[60:63], s[36:37]
	v_cvt_pk_bf16_f32 v52, v52, v53
	v_cvt_pk_bf16_f32 v53, v54, v55
	v_cvt_pk_bf16_f32 v54, v48, v49
	v_cvt_pk_bf16_f32 v55, v50, v51
	global_store_dwordx4 v142, v[52:55], s[36:37] offset:64
	v_mul_f32_e32 v143, v45, v45
	v_mul_f32_e32 v144, v47, v47
	v_fmac_f32_e32 v143, v44, v44
	v_fmac_f32_e32 v144, v46, v46
	v_add_f32_e32 v142, v143, v144
	v_mul_f32_e32 v143, v41, v41
	v_mul_f32_e32 v144, v43, v43
	v_fmac_f32_e32 v143, v40, v40
	v_fmac_f32_e32 v144, v42, v42
	v_add_f32_e32 v143, v143, v144
	v_add_f32_e32 v142, v142, v143
	v_mul_f32_e32 v143, v37, v37
	v_mul_f32_e32 v144, v39, v39
	v_fmac_f32_e32 v143, v36, v36
	v_fmac_f32_e32 v144, v38, v38
	v_add_f32_e32 v143, v143, v144
	v_add_f32_e32 v142, v142, v143
	v_mul_f32_e32 v143, v33, v33
	v_mul_f32_e32 v144, v35, v35
	v_fmac_f32_e32 v143, v32, v32
	v_fmac_f32_e32 v144, v34, v34
	v_add_f32_e32 v143, v143, v144
	v_add_f32_e32 v142, v142, v143
	v_mov_b32_e32 v143, v142
	s_nop 1
	v_permlane16_swap_b32_e32 v142, v143
	v_add_f32_e32 v142, v142, v143
	v_mov_b32_e32 v143, v142
	s_nop 1
	v_permlane32_swap_b32_e32 v142, v143
	v_add_f32_e32 v142, v142, v143
	v_fmamk_f32 v144, v142, 0x3c800000, v153
	v_rsq_f32_e32 v144, v144
	s_nop 0
	v_mul_f32_e32 v44, v44, v144
	v_mul_f32_e32 v45, v45, v144
	v_mul_f32_e32 v46, v46, v144
	v_mul_f32_e32 v47, v47, v144
	v_mul_f32_e32 v44, v44, v162
	v_mul_f32_e32 v45, v45, v163
	v_mul_f32_e32 v46, v46, v164
	v_mul_f32_e32 v47, v47, v165
	v_mul_f32_e32 v40, v40, v144
	v_mul_f32_e32 v41, v41, v144
	v_mul_f32_e32 v42, v42, v144
	v_mul_f32_e32 v43, v43, v144
	v_mul_f32_e32 v40, v40, v166
	v_mul_f32_e32 v41, v41, v167
	v_mul_f32_e32 v42, v42, v168
	v_mul_f32_e32 v43, v43, v169
	v_mul_f32_e32 v36, v36, v144
	v_mul_f32_e32 v37, v37, v144
	v_mul_f32_e32 v38, v38, v144
	v_mul_f32_e32 v39, v39, v144
	v_mul_f32_e32 v36, v36, v170
	v_mul_f32_e32 v37, v37, v171
	v_mul_f32_e32 v38, v38, v172
	v_mul_f32_e32 v39, v39, v173
	v_mul_f32_e32 v32, v32, v144
	v_mul_f32_e32 v33, v33, v144
	v_mul_f32_e32 v34, v34, v144
	v_mul_f32_e32 v35, v35, v144
	v_mul_f32_e32 v32, v32, v174
	v_mul_f32_e32 v33, v33, v175
	v_mul_f32_e32 v34, v34, v176
	v_mul_f32_e32 v35, v35, v177
	v_lshl_add_u32 v142, s12, 8, v158
	v_add_u32_e32 v142, 144, v142
	v_lshl_add_u32 v142, v142, s13, v154
	v_cvt_pk_bf16_f32 v44, v44, v45
	v_cvt_pk_bf16_f32 v45, v46, v47
	v_cvt_pk_bf16_f32 v46, v40, v41
	v_cvt_pk_bf16_f32 v47, v42, v43
	global_store_dwordx4 v142, v[44:47], s[36:37]
	v_cvt_pk_bf16_f32 v36, v36, v37
	v_cvt_pk_bf16_f32 v37, v38, v39
	v_cvt_pk_bf16_f32 v38, v32, v33
	v_cvt_pk_bf16_f32 v39, v34, v35
	global_store_dwordx4 v142, v[36:39], s[36:37] offset:64
	v_mul_f32_e32 v143, v29, v29
; __device__ __forceinline__ unsigned pkbf(float lo, float hi) { f32x2_t v = {lo, hi}; bf16x2_t b = __builtin_convertvector(v, bf16x2_t); return __builtin_bit_cast(unsigned, b); }
;     __device__ __forceinline__ void operator()(const f32x4 (&acc)[2][2][4][2], const pg8::Unit& u, int wr, int wc, int fr, int fq) const {
;     ...
;                 const int row = rbase + ai * 128 + m * 16;
;                 float rs = 1.0f;
;                 if (kind < 2) {
;                     float ss = 0.f;
; #pragma unroll
;                     for (int bj = 0; bj < 2; ++bj)
; #pragma unroll
;                         for (int n = 0; n < 2; ++n) { const f32x4 x = acc[ai][bj][m][n]; ss += (x[0] * x[0] + x[1] * x[1]) + (x[2] * x[2] + x[3] * x[3]); }
;                     ss = xsum4(ss);
;                     rs = rsqrtf(ss * (1.0f / 64.0f) + EPS);
;                 }
;                 const int t = row & (SEQ - 1);
; #pragma unroll
;                 for (int bj = 0; bj < 2; ++bj) {
;                     f32x4 v0 = acc[ai][bj][m][0], v1 = acc[ai][bj][m][1];
;                     if (kind < 2) {
;                         v0 = v0 * rs * *(const f32x4*)(gp + 32 * bj); v1 = v1 * rs * *(const f32x4*)(gp + 32 * bj + 4);
;                         if (dorope) {
;                             const int pos = bj ? (t & 63) : (t >> 6);
;                             const f32x4 c0 = *(const f32x4*)(rp + pos * 16), c1 = *(const f32x4*)(rp + pos * 16 + 4);
;                             const f32x4 s0 = *(const f32x4*)(rp + 2048 + pos * 16), s1 = *(const f32x4*)(rp + 2048 + pos * 16 + 4);
;                             f32x4 o0, o1;
; #pragma unroll
;                             for (int i = 0; i < 4; ++i) { const float p0 = __uint_as_float((unsigned)__builtin_amdgcn_ds_bpermute(paddr, (int)__float_as_uint(v0[i]))) * s0[i], p1 = __uint_as_float((unsigned)__builtin_amdgcn_ds_bpermute(paddr, (int)__float_as_uint(v1[i]))) * s1[i];
;                                 o0[i] = v0[i] * c0[i] + (fq >= 2 ? p0 : -p0); o1[i] = v1[i] * c1[i] + (fq >= 2 ? p1 : -p1); }
;                             v0 = o0; v1 = o1;
;                         }
;                     }
;                     u32x4 w; w.x = pkbf(v0[0], v0[1]); w.y = pkbf(v0[2], v0[3]); w.z = pkbf(v1[0], v1[1]); w.w = pkbf(v1[2], v1[3]);
;                     *(u32x4*)(dst + (size_t)row * pitch + 32 * bj) = w;
;                 }
	v_mul_f32_e32 v144, v31, v31
	v_fmac_f32_e32 v143, v28, v28
	v_fmac_f32_e32 v144, v30, v30
	v_add_f32_e32 v142, v143, v144
	v_mul_f32_e32 v143, v25, v25
	v_mul_f32_e32 v144, v27, v27
	v_fmac_f32_e32 v143, v24, v24
	v_fmac_f32_e32 v144, v26, v26
	v_add_f32_e32 v143, v143, v144
	v_add_f32_e32 v142, v142, v143
	v_mul_f32_e32 v143, v21, v21
	v_mul_f32_e32 v144, v23, v23
	v_fmac_f32_e32 v143, v20, v20
	v_fmac_f32_e32 v144, v22, v22
	v_add_f32_e32 v143, v143, v144
	v_add_f32_e32 v142, v142, v143
	v_mul_f32_e32 v143, v17, v17
	v_mul_f32_e32 v144, v19, v19
	v_fmac_f32_e32 v143, v16, v16
	v_fmac_f32_e32 v144, v18, v18
	v_add_f32_e32 v143, v143, v144
	v_add_f32_e32 v142, v142, v143
	v_mov_b32_e32 v143, v142
	s_nop 1
	v_permlane16_swap_b32_e32 v142, v143
	v_add_f32_e32 v142, v142, v143
	v_mov_b32_e32 v143, v142
	s_nop 1
	v_permlane32_swap_b32_e32 v142, v143
	v_add_f32_e32 v142, v142, v143
	v_fmamk_f32 v144, v142, 0x3c800000, v153
	v_rsq_f32_e32 v144, v144
	s_nop 0
	v_mul_f32_e32 v28, v28, v144
	v_mul_f32_e32 v29, v29, v144
	v_mul_f32_e32 v30, v30, v144
	v_mul_f32_e32 v31, v31, v144
	v_mul_f32_e32 v28, v28, v162
	v_mul_f32_e32 v29, v29, v163
	v_mul_f32_e32 v30, v30, v164
	v_mul_f32_e32 v31, v31, v165
	v_mul_f32_e32 v24, v24, v144
	v_mul_f32_e32 v25, v25, v144
	v_mul_f32_e32 v26, v26, v144
	v_mul_f32_e32 v27, v27, v144
	v_mul_f32_e32 v24, v24, v166
	v_mul_f32_e32 v25, v25, v167
	v_mul_f32_e32 v26, v26, v168
	v_mul_f32_e32 v27, v27, v169
	v_mul_f32_e32 v20, v20, v144
	v_mul_f32_e32 v21, v21, v144
	v_mul_f32_e32 v22, v22, v144
	v_mul_f32_e32 v23, v23, v144
	v_mul_f32_e32 v20, v20, v170
	v_mul_f32_e32 v21, v21, v171
	v_mul_f32_e32 v22, v22, v172
	v_mul_f32_e32 v23, v23, v173
	v_mul_f32_e32 v16, v16, v144
	v_mul_f32_e32 v17, v17, v144
	v_mul_f32_e32 v18, v18, v144
	v_mul_f32_e32 v19, v19, v144
	v_mul_f32_e32 v16, v16, v174
	v_mul_f32_e32 v17, v17, v175
	v_mul_f32_e32 v18, v18, v176
	v_mul_f32_e32 v19, v19, v177
	v_lshl_add_u32 v142, s12, 8, v158
	v_add_u32_e32 v142, 160, v142
	v_lshl_add_u32 v142, v142, s13, v154
	v_cvt_pk_bf16_f32 v28, v28, v29
	v_cvt_pk_bf16_f32 v29, v30, v31
	v_cvt_pk_bf16_f32 v30, v24, v25
	v_cvt_pk_bf16_f32 v31, v26, v27
	global_store_dwordx4 v142, v[28:31], s[36:37]
	v_cvt_pk_bf16_f32 v20, v20, v21
	v_cvt_pk_bf16_f32 v21, v22, v23
	v_cvt_pk_bf16_f32 v22, v16, v17
	v_cvt_pk_bf16_f32 v23, v18, v19
	global_store_dwordx4 v142, v[20:23], s[36:37] offset:64
	v_mul_f32_e32 v143, v13, v13
	v_mul_f32_e32 v144, v15, v15
	v_fmac_f32_e32 v143, v12, v12
	v_fmac_f32_e32 v144, v14, v14
	v_add_f32_e32 v142, v143, v144
	v_mul_f32_e32 v143, v9, v9
	v_mul_f32_e32 v144, v11, v11
	v_fmac_f32_e32 v143, v8, v8
	v_fmac_f32_e32 v144, v10, v10
	v_add_f32_e32 v143, v143, v144
	v_add_f32_e32 v142, v142, v143
	v_mul_f32_e32 v143, v5, v5
	v_mul_f32_e32 v144, v7, v7
	v_fmac_f32_e32 v143, v4, v4
	v_fmac_f32_e32 v144, v6, v6
	v_add_f32_e32 v143, v143, v144
	v_add_f32_e32 v142, v142, v143
	v_mul_f32_e32 v143, v1, v1
	v_mul_f32_e32 v144, v3, v3
	v_fmac_f32_e32 v143, v0, v0
	v_fmac_f32_e32 v144, v2, v2
	v_add_f32_e32 v143, v143, v144
	v_add_f32_e32 v142, v142, v143
	v_mov_b32_e32 v143, v142
	s_nop 1
	v_permlane16_swap_b32_e32 v142, v143
	v_add_f32_e32 v142, v142, v143
	v_mov_b32_e32 v143, v142
	s_nop 1
	v_permlane32_swap_b32_e32 v142, v143
	v_add_f32_e32 v142, v142, v143
	v_fmamk_f32 v144, v142, 0x3c800000, v153
	v_rsq_f32_e32 v144, v144
	s_nop 0
	v_mul_f32_e32 v12, v12, v144
	v_mul_f32_e32 v13, v13, v144
	v_mul_f32_e32 v14, v14, v144
	v_mul_f32_e32 v15, v15, v144
	v_mul_f32_e32 v12, v12, v162
	v_mul_f32_e32 v13, v13, v163
	v_mul_f32_e32 v14, v14, v164
	v_mul_f32_e32 v15, v15, v165
	v_mul_f32_e32 v8, v8, v144
	v_mul_f32_e32 v9, v9, v144
	v_mul_f32_e32 v10, v10, v144
	v_mul_f32_e32 v11, v11, v144
	v_mul_f32_e32 v8, v8, v166
	v_mul_f32_e32 v9, v9, v167
	v_mul_f32_e32 v10, v10, v168
	v_mul_f32_e32 v11, v11, v169
	v_mul_f32_e32 v4, v4, v144
	v_mul_f32_e32 v5, v5, v144
	v_mul_f32_e32 v6, v6, v144
	v_mul_f32_e32 v7, v7, v144
	v_mul_f32_e32 v4, v4, v170
	v_mul_f32_e32 v5, v5, v171
	v_mul_f32_e32 v6, v6, v172
	v_mul_f32_e32 v7, v7, v173
	v_mul_f32_e32 v0, v0, v144
	v_mul_f32_e32 v1, v1, v144
	v_mul_f32_e32 v2, v2, v144
	v_mul_f32_e32 v3, v3, v144
	v_mul_f32_e32 v0, v0, v174
	v_mul_f32_e32 v1, v1, v175
	v_mul_f32_e32 v2, v2, v176
	v_mul_f32_e32 v3, v3, v177
	v_lshl_add_u32 v142, s12, 8, v158
	v_add_u32_e32 v142, 176, v142
	v_lshl_add_u32 v142, v142, s13, v154
	v_cvt_pk_bf16_f32 v12, v12, v13
	v_cvt_pk_bf16_f32 v13, v14, v15
	v_cvt_pk_bf16_f32 v14, v8, v9
	v_cvt_pk_bf16_f32 v15, v10, v11
	global_store_dwordx4 v142, v[12:15], s[36:37]
	v_cvt_pk_bf16_f32 v4, v4, v5
	v_cvt_pk_bf16_f32 v5, v6, v7
	v_cvt_pk_bf16_f32 v6, v0, v1
	v_cvt_pk_bf16_f32 v7, v2, v3
	global_store_dwordx4 v142, v[4:7], s[36:37] offset:64
	s_branch .Lqkv_join

; __device__ __forceinline__ unsigned pkbf(float lo, float hi) { f32x2_t v = {lo, hi}; bf16x2_t b = __builtin_convertvector(v, bf16x2_t); return __builtin_bit_cast(unsigned, b); }
;     __device__ __forceinline__ void operator()(const f32x4 (&acc)[2][2][4][2], const pg8::Unit& u, int wr, int wc, int fr, int fq) const {
;     ...
;                 const int t = row & (SEQ - 1);
; #pragma unroll
;                 for (int bj = 0; bj < 2; ++bj) {
;                     f32x4 v0 = acc[ai][bj][m][0], v1 = acc[ai][bj][m][1];
;                     if (kind < 2) {
;                         v0 = v0 * rs * *(const f32x4*)(gp + 32 * bj); v1 = v1 * rs * *(const f32x4*)(gp + 32 * bj + 4);
;                         if (dorope) {
;                             const int pos = bj ? (t & 63) : (t >> 6);
;                             const f32x4 c0 = *(const f32x4*)(rp + pos * 16), c1 = *(const f32x4*)(rp + pos * 16 + 4);
;                             const f32x4 s0 = *(const f32x4*)(rp + 2048 + pos * 16), s1 = *(const f32x4*)(rp + 2048 + pos * 16 + 4);
;                             f32x4 o0, o1;
; #pragma unroll
;                             for (int i = 0; i < 4; ++i) { const float p0 = __uint_as_float((unsigned)__builtin_amdgcn_ds_bpermute(paddr, (int)__float_as_uint(v0[i]))) * s0[i], p1 = __uint_as_float((unsigned)__builtin_amdgcn_ds_bpermute(paddr, (int)__float_as_uint(v1[i]))) * s1[i];
;                                 o0[i] = v0[i] * c0[i] + (fq >= 2 ? p0 : -p0); o1[i] = v1[i] * c1[i] + (fq >= 2 ? p1 : -p1); }
;                             v0 = o0; v1 = o1;
;                         }
;                     }
;                     u32x4 w; w.x = pkbf(v0[0], v0[1]); w.y = pkbf(v0[2], v0[3]); w.z = pkbf(v1[0], v1[1]); w.w = pkbf(v1[2], v1[3]);
;                     *(u32x4*)(dst + (size_t)row * pitch + 32 * bj) = w;
.Lqkv_rope:
	v_lshl_add_u64 v[214:215], v[136:137], 0, s[82:83]
	global_load_dwordx4 v[162:165], v[214:215], off
	global_load_dwordx4 v[166:169], v[214:215], off offset:16
	global_load_dwordx4 v[170:173], v[214:215], off offset:128
	global_load_dwordx4 v[174:177], v[214:215], off offset:144
	v_lshl_add_u32 v221, s12, 8, v158
	v_and_b32_e32 v218, 0x1fc0, v221
	v_mov_b32_e32 v219, 0
	v_lshl_add_u64 v[214:215], v[138:139], 0, v[218:219]
	v_lshl_add_u64 v[216:217], v[140:141], 0, v[218:219]
	global_load_dwordx4 v[178:181], v[214:215], off
	global_load_dwordx4 v[182:185], v[214:215], off offset:16
	global_load_dwordx4 v[186:189], v[216:217], off
	global_load_dwordx4 v[190:193], v[216:217], off offset:16
	v_and_b32_e32 v218, 63, v221
	v_lshlrev_b32_e32 v218, 6, v218
	v_mov_b32_e32 v219, 0
	v_lshl_add_u64 v[214:215], v[138:139], 0, v[218:219]
	v_lshl_add_u64 v[216:217], v[140:141], 0, v[218:219]
	global_load_dwordx4 v[198:201], v[214:215], off
	global_load_dwordx4 v[202:205], v[214:215], off offset:16
	global_load_dwordx4 v[206:209], v[216:217], off
	global_load_dwordx4 v[210:213], v[216:217], off offset:16
	v_mul_f32_e32 v143, v125, v125
	v_mul_f32_e32 v144, v127, v127
	v_fmac_f32_e32 v143, v124, v124
	v_fmac_f32_e32 v144, v126, v126
	v_add_f32_e32 v142, v143, v144
	v_mul_f32_e32 v143, v121, v121
	v_mul_f32_e32 v144, v123, v123
	v_fmac_f32_e32 v143, v120, v120
	v_fmac_f32_e32 v144, v122, v122
	v_add_f32_e32 v143, v143, v144
	v_add_f32_e32 v142, v142, v143
	v_mul_f32_e32 v143, v117, v117
	v_mul_f32_e32 v144, v119, v119
	v_fmac_f32_e32 v143, v116, v116
	v_fmac_f32_e32 v144, v118, v118
	v_add_f32_e32 v143, v143, v144
	v_add_f32_e32 v142, v142, v143
	v_mul_f32_e32 v143, v113, v113
	v_mul_f32_e32 v144, v115, v115
	v_fmac_f32_e32 v143, v112, v112
	v_fmac_f32_e32 v144, v114, v114
	v_add_f32_e32 v143, v143, v144
	v_add_f32_e32 v142, v142, v143
	v_mov_b32_e32 v143, v142
	s_nop 1
	v_permlane16_swap_b32_e32 v142, v143
	v_add_f32_e32 v142, v142, v143
	v_mov_b32_e32 v143, v142
	s_nop 1
	v_permlane32_swap_b32_e32 v142, v143
	v_add_f32_e32 v142, v142, v143
	v_fmamk_f32 v144, v142, 0x3c800000, v153
	v_rsq_f32_e32 v144, v144
	s_nop 0
	s_waitcnt vmcnt(8)
	v_mul_f32_e32 v124, v124, v144
	v_mul_f32_e32 v125, v125, v144
	v_mul_f32_e32 v126, v126, v144
	v_mul_f32_e32 v127, v127, v144
	v_mul_f32_e32 v124, v124, v162
	v_mul_f32_e32 v125, v125, v163
	v_mul_f32_e32 v126, v126, v164
	v_mul_f32_e32 v127, v127, v165
	v_mul_f32_e32 v120, v120, v144
	v_mul_f32_e32 v121, v121, v144
	v_mul_f32_e32 v122, v122, v144
	v_mul_f32_e32 v123, v123, v144
	v_mul_f32_e32 v120, v120, v166
	v_mul_f32_e32 v121, v121, v167
	v_mul_f32_e32 v122, v122, v168
	v_mul_f32_e32 v123, v123, v169
	v_mul_f32_e32 v116, v116, v144
	v_mul_f32_e32 v117, v117, v144
	v_mul_f32_e32 v118, v118, v144
	v_mul_f32_e32 v119, v119, v144
	v_mul_f32_e32 v116, v116, v170
	v_mul_f32_e32 v117, v117, v171
	v_mul_f32_e32 v118, v118, v172
	v_mul_f32_e32 v119, v119, v173
	v_mul_f32_e32 v112, v112, v144
	v_mul_f32_e32 v113, v113, v144
	v_mul_f32_e32 v114, v114, v144
	v_mul_f32_e32 v115, v115, v144
	v_mul_f32_e32 v112, v112, v174
	v_mul_f32_e32 v113, v113, v175
	v_mul_f32_e32 v114, v114, v176
	v_mul_f32_e32 v115, v115, v177
	ds_bpermute_b32 v214, v160, v124
	ds_bpermute_b32 v215, v160, v125
	ds_bpermute_b32 v216, v160, v126
	ds_bpermute_b32 v217, v160, v127
	ds_bpermute_b32 v218, v160, v120
	ds_bpermute_b32 v219, v160, v121
	ds_bpermute_b32 v220, v160, v122
	ds_bpermute_b32 v221, v160, v123
	s_waitcnt vmcnt(4)
	s_waitcnt lgkmcnt(0)
	v_mul_f32_e32 v214, v186, v214
	v_mul_f32_e32 v215, v187, v215
	v_mul_f32_e32 v216, v188, v216
	v_mul_f32_e32 v217, v189, v217
	v_cndmask_b32_e64 v214, -v214, v214, s[6:7]
	v_cndmask_b32_e64 v215, -v215, v215, s[6:7]
	v_cndmask_b32_e64 v216, -v216, v216, s[6:7]
	v_cndmask_b32_e64 v217, -v217, v217, s[6:7]
	v_fma_f32 v124, v124, v178, v214
	v_fma_f32 v125, v125, v179, v215
	v_fma_f32 v126, v126, v180, v216
	v_fma_f32 v127, v127, v181, v217
	v_mul_f32_e32 v218, v190, v218
	v_mul_f32_e32 v219, v191, v219
	v_mul_f32_e32 v220, v192, v220
	v_mul_f32_e32 v221, v193, v221
	v_cndmask_b32_e64 v218, -v218, v218, s[6:7]
	v_cndmask_b32_e64 v219, -v219, v219, s[6:7]
	v_cndmask_b32_e64 v220, -v220, v220, s[6:7]
	v_cndmask_b32_e64 v221, -v221, v221, s[6:7]
	v_fma_f32 v120, v120, v182, v218
	v_fma_f32 v121, v121, v183, v219
	v_fma_f32 v122, v122, v184, v220
	v_fma_f32 v123, v123, v185, v221
	v_lshl_add_u32 v142, s12, 8, v158
	v_lshl_add_u32 v142, v142, s13, v154
	v_cvt_pk_bf16_f32 v124, v124, v125
	v_cvt_pk_bf16_f32 v125, v126, v127
	v_cvt_pk_bf16_f32 v126, v120, v121
	v_cvt_pk_bf16_f32 v127, v122, v123
	global_store_dwordx4 v142, v[124:127], s[36:37]
	ds_bpermute_b32 v214, v160, v116
	ds_bpermute_b32 v215, v160, v117
	ds_bpermute_b32 v216, v160, v118
	ds_bpermute_b32 v217, v160, v119
	ds_bpermute_b32 v218, v160, v112
	ds_bpermute_b32 v219, v160, v113
	ds_bpermute_b32 v220, v160, v114
	ds_bpermute_b32 v221, v160, v115
	s_waitcnt vmcnt(1)
	s_waitcnt lgkmcnt(0)
; __device__ __forceinline__ unsigned pkbf(float lo, float hi) { f32x2_t v = {lo, hi}; bf16x2_t b = __builtin_convertvector(v, bf16x2_t); return __builtin_bit_cast(unsigned, b); }
;     __device__ __forceinline__ void operator()(const f32x4 (&acc)[2][2][4][2], const pg8::Unit& u, int wr, int wc, int fr, int fq) const {
;     ...
;                 const int t = row & (SEQ - 1);
; #pragma unroll
;                 for (int bj = 0; bj < 2; ++bj) {
;                     f32x4 v0 = acc[ai][bj][m][0], v1 = acc[ai][bj][m][1];
;                     if (kind < 2) {
;                         v0 = v0 * rs * *(const f32x4*)(gp + 32 * bj); v1 = v1 * rs * *(const f32x4*)(gp + 32 * bj + 4);
;                         if (dorope) {
;                             const int pos = bj ? (t & 63) : (t >> 6);
;                             const f32x4 c0 = *(const f32x4*)(rp + pos * 16), c1 = *(const f32x4*)(rp + pos * 16 + 4);
;                             const f32x4 s0 = *(const f32x4*)(rp + 2048 + pos * 16), s1 = *(const f32x4*)(rp + 2048 + pos * 16 + 4);
;                             f32x4 o0, o1;
; #pragma unroll
;                             for (int i = 0; i < 4; ++i) { const float p0 = __uint_as_float((unsigned)__builtin_amdgcn_ds_bpermute(paddr, (int)__float_as_uint(v0[i]))) * s0[i], p1 = __uint_as_float((unsigned)__builtin_amdgcn_ds_bpermute(paddr, (int)__float_as_uint(v1[i]))) * s1[i];
;                                 o0[i] = v0[i] * c0[i] + (fq >= 2 ? p0 : -p0); o1[i] = v1[i] * c1[i] + (fq >= 2 ? p1 : -p1); }
;                             v0 = o0; v1 = o1;
;                         }
;                     }
;                     u32x4 w; w.x = pkbf(v0[0], v0[1]); w.y = pkbf(v0[2], v0[3]); w.z = pkbf(v1[0], v1[1]); w.w = pkbf(v1[2], v1[3]);
;                     *(u32x4*)(dst + (size_t)row * pitch + 32 * bj) = w;
	v_mul_f32_e32 v214, v206, v214
	v_mul_f32_e32 v215, v207, v215
	v_mul_f32_e32 v216, v208, v216
	v_mul_f32_e32 v217, v209, v217
	v_cndmask_b32_e64 v214, -v214, v214, s[6:7]
	v_cndmask_b32_e64 v215, -v215, v215, s[6:7]
	v_cndmask_b32_e64 v216, -v216, v216, s[6:7]
	v_cndmask_b32_e64 v217, -v217, v217, s[6:7]
	v_fma_f32 v116, v116, v198, v214
	v_fma_f32 v117, v117, v199, v215
	v_fma_f32 v118, v118, v200, v216
	v_fma_f32 v119, v119, v201, v217
	v_mul_f32_e32 v218, v210, v218
	v_mul_f32_e32 v219, v211, v219
	v_mul_f32_e32 v220, v212, v220
	v_mul_f32_e32 v221, v213, v221
	v_cndmask_b32_e64 v218, -v218, v218, s[6:7]
	v_cndmask_b32_e64 v219, -v219, v219, s[6:7]
	v_cndmask_b32_e64 v220, -v220, v220, s[6:7]
	v_cndmask_b32_e64 v221, -v221, v221, s[6:7]
	v_fma_f32 v112, v112, v202, v218
	v_fma_f32 v113, v113, v203, v219
	v_fma_f32 v114, v114, v204, v220
	v_fma_f32 v115, v115, v205, v221
	v_cvt_pk_bf16_f32 v116, v116, v117
	v_cvt_pk_bf16_f32 v117, v118, v119
	v_cvt_pk_bf16_f32 v118, v112, v113
	v_cvt_pk_bf16_f32 v119, v114, v115
	global_store_dwordx4 v142, v[116:119], s[36:37] offset:64
	v_lshl_add_u32 v221, s12, 8, v158
	v_add_u32_e32 v221, 16, v221
	v_and_b32_e32 v218, 63, v221
	v_lshlrev_b32_e32 v218, 6, v218
	v_mov_b32_e32 v219, 0
	v_lshl_add_u64 v[214:215], v[138:139], 0, v[218:219]
	v_lshl_add_u64 v[216:217], v[140:141], 0, v[218:219]
	global_load_dwordx4 v[198:201], v[214:215], off
	global_load_dwordx4 v[202:205], v[214:215], off offset:16
	global_load_dwordx4 v[206:209], v[216:217], off
	global_load_dwordx4 v[210:213], v[216:217], off offset:16
	v_mul_f32_e32 v143, v109, v109
	v_mul_f32_e32 v144, v111, v111
	v_fmac_f32_e32 v143, v108, v108
	v_fmac_f32_e32 v144, v110, v110
	v_add_f32_e32 v142, v143, v144
	v_mul_f32_e32 v143, v105, v105
	v_mul_f32_e32 v144, v107, v107
	v_fmac_f32_e32 v143, v104, v104
	v_fmac_f32_e32 v144, v106, v106
	v_add_f32_e32 v143, v143, v144
	v_add_f32_e32 v142, v142, v143
	v_mul_f32_e32 v143, v101, v101
	v_mul_f32_e32 v144, v103, v103
	v_fmac_f32_e32 v143, v100, v100
	v_fmac_f32_e32 v144, v102, v102
	v_add_f32_e32 v143, v143, v144
	v_add_f32_e32 v142, v142, v143
	v_mul_f32_e32 v143, v97, v97
	v_mul_f32_e32 v144, v99, v99
	v_fmac_f32_e32 v143, v96, v96
	v_fmac_f32_e32 v144, v98, v98
	v_add_f32_e32 v143, v143, v144
	v_add_f32_e32 v142, v142, v143
	v_mov_b32_e32 v143, v142
	s_nop 1
	v_permlane16_swap_b32_e32 v142, v143
	v_add_f32_e32 v142, v142, v143
	v_mov_b32_e32 v143, v142
	s_nop 1
	v_permlane32_swap_b32_e32 v142, v143
	v_add_f32_e32 v142, v142, v143
	v_fmamk_f32 v144, v142, 0x3c800000, v153
	v_rsq_f32_e32 v144, v144
	s_nop 0
	v_mul_f32_e32 v108, v108, v144
	v_mul_f32_e32 v109, v109, v144
	v_mul_f32_e32 v110, v110, v144
	v_mul_f32_e32 v111, v111, v144
	v_mul_f32_e32 v108, v108, v162
	v_mul_f32_e32 v109, v109, v163
	v_mul_f32_e32 v110, v110, v164
	v_mul_f32_e32 v111, v111, v165
	v_mul_f32_e32 v104, v104, v144
	v_mul_f32_e32 v105, v105, v144
	v_mul_f32_e32 v106, v106, v144
	v_mul_f32_e32 v107, v107, v144
	v_mul_f32_e32 v104, v104, v166
	v_mul_f32_e32 v105, v105, v167
	v_mul_f32_e32 v106, v106, v168
	v_mul_f32_e32 v107, v107, v169
	v_mul_f32_e32 v100, v100, v144
	v_mul_f32_e32 v101, v101, v144
	v_mul_f32_e32 v102, v102, v144
	v_mul_f32_e32 v103, v103, v144
	v_mul_f32_e32 v100, v100, v170
	v_mul_f32_e32 v101, v101, v171
	v_mul_f32_e32 v102, v102, v172
	v_mul_f32_e32 v103, v103, v173
	v_mul_f32_e32 v96, v96, v144
	v_mul_f32_e32 v97, v97, v144
	v_mul_f32_e32 v98, v98, v144
	v_mul_f32_e32 v99, v99, v144
	v_mul_f32_e32 v96, v96, v174
	v_mul_f32_e32 v97, v97, v175
	v_mul_f32_e32 v98, v98, v176
	v_mul_f32_e32 v99, v99, v177
	ds_bpermute_b32 v214, v160, v108
	ds_bpermute_b32 v215, v160, v109
	ds_bpermute_b32 v216, v160, v110
	ds_bpermute_b32 v217, v160, v111
	ds_bpermute_b32 v218, v160, v104
	ds_bpermute_b32 v219, v160, v105
	ds_bpermute_b32 v220, v160, v106
	ds_bpermute_b32 v221, v160, v107
	s_waitcnt lgkmcnt(0)
	v_mul_f32_e32 v214, v186, v214
	v_mul_f32_e32 v215, v187, v215
	v_mul_f32_e32 v216, v188, v216
	v_mul_f32_e32 v217, v189, v217
	v_cndmask_b32_e64 v214, -v214, v214, s[6:7]
	v_cndmask_b32_e64 v215, -v215, v215, s[6:7]
	v_cndmask_b32_e64 v216, -v216, v216, s[6:7]
	v_cndmask_b32_e64 v217, -v217, v217, s[6:7]
	v_fma_f32 v108, v108, v178, v214
	v_fma_f32 v109, v109, v179, v215
	v_fma_f32 v110, v110, v180, v216
	v_fma_f32 v111, v111, v181, v217
	v_mul_f32_e32 v218, v190, v218
	v_mul_f32_e32 v219, v191, v219
	v_mul_f32_e32 v220, v192, v220
	v_mul_f32_e32 v221, v193, v221
	v_cndmask_b32_e64 v218, -v218, v218, s[6:7]
	v_cndmask_b32_e64 v219, -v219, v219, s[6:7]
	v_cndmask_b32_e64 v220, -v220, v220, s[6:7]
	v_cndmask_b32_e64 v221, -v221, v221, s[6:7]
	v_fma_f32 v104, v104, v182, v218
	v_fma_f32 v105, v105, v183, v219
	v_fma_f32 v106, v106, v184, v220
	v_fma_f32 v107, v107, v185, v221
	v_lshl_add_u32 v142, s12, 8, v158
	v_add_u32_e32 v142, 16, v142
	v_lshl_add_u32 v142, v142, s13, v154
	v_cvt_pk_bf16_f32 v108, v108, v109
	v_cvt_pk_bf16_f32 v109, v110, v111
	v_cvt_pk_bf16_f32 v110, v104, v105
	v_cvt_pk_bf16_f32 v111, v106, v107
	global_store_dwordx4 v142, v[108:111], s[36:37]
	ds_bpermute_b32 v214, v160, v100
	ds_bpermute_b32 v215, v160, v101
	ds_bpermute_b32 v216, v160, v102
	ds_bpermute_b32 v217, v160, v103
	ds_bpermute_b32 v218, v160, v96
	ds_bpermute_b32 v219, v160, v97
	ds_bpermute_b32 v220, v160, v98
	ds_bpermute_b32 v221, v160, v99
	s_waitcnt vmcnt(1)
	s_waitcnt lgkmcnt(0)
; __device__ __forceinline__ unsigned pkbf(float lo, float hi) { f32x2_t v = {lo, hi}; bf16x2_t b = __builtin_convertvector(v, bf16x2_t); return __builtin_bit_cast(unsigned, b); }
;     __device__ __forceinline__ void operator()(const f32x4 (&acc)[2][2][4][2], const pg8::Unit& u, int wr, int wc, int fr, int fq) const {
;     ...
;                 const int t = row & (SEQ - 1);
; #pragma unroll
;                 for (int bj = 0; bj < 2; ++bj) {
;                     f32x4 v0 = acc[ai][bj][m][0], v1 = acc[ai][bj][m][1];
;                     if (kind < 2) {
;                         v0 = v0 * rs * *(const f32x4*)(gp + 32 * bj); v1 = v1 * rs * *(const f32x4*)(gp + 32 * bj + 4);
;                         if (dorope) {
;                             const int pos = bj ? (t & 63) : (t >> 6);
;                             const f32x4 c0 = *(const f32x4*)(rp + pos * 16), c1 = *(const f32x4*)(rp + pos * 16 + 4);
;                             const f32x4 s0 = *(const f32x4*)(rp + 2048 + pos * 16), s1 = *(const f32x4*)(rp + 2048 + pos * 16 + 4);
;                             f32x4 o0, o1;
; #pragma unroll
;                             for (int i = 0; i < 4; ++i) { const float p0 = __uint_as_float((unsigned)__builtin_amdgcn_ds_bpermute(paddr, (int)__float_as_uint(v0[i]))) * s0[i], p1 = __uint_as_float((unsigned)__builtin_amdgcn_ds_bpermute(paddr, (int)__float_as_uint(v1[i]))) * s1[i];
;                                 o0[i] = v0[i] * c0[i] + (fq >= 2 ? p0 : -p0); o1[i] = v1[i] * c1[i] + (fq >= 2 ? p1 : -p1); }
;                             v0 = o0; v1 = o1;
;                         }
;                     }
;                     u32x4 w; w.x = pkbf(v0[0], v0[1]); w.y = pkbf(v0[2], v0[3]); w.z = pkbf(v1[0], v1[1]); w.w = pkbf(v1[2], v1[3]);
;                     *(u32x4*)(dst + (size_t)row * pitch + 32 * bj) = w;
	v_mul_f32_e32 v214, v206, v214
	v_mul_f32_e32 v215, v207, v215
	v_mul_f32_e32 v216, v208, v216
	v_mul_f32_e32 v217, v209, v217
	v_cndmask_b32_e64 v214, -v214, v214, s[6:7]
	v_cndmask_b32_e64 v215, -v215, v215, s[6:7]
	v_cndmask_b32_e64 v216, -v216, v216, s[6:7]
	v_cndmask_b32_e64 v217, -v217, v217, s[6:7]
	v_fma_f32 v100, v100, v198, v214
	v_fma_f32 v101, v101, v199, v215
	v_fma_f32 v102, v102, v200, v216
	v_fma_f32 v103, v103, v201, v217
	v_mul_f32_e32 v218, v210, v218
	v_mul_f32_e32 v219, v211, v219
	v_mul_f32_e32 v220, v212, v220
	v_mul_f32_e32 v221, v213, v221
	v_cndmask_b32_e64 v218, -v218, v218, s[6:7]
	v_cndmask_b32_e64 v219, -v219, v219, s[6:7]
	v_cndmask_b32_e64 v220, -v220, v220, s[6:7]
	v_cndmask_b32_e64 v221, -v221, v221, s[6:7]
	v_fma_f32 v96, v96, v202, v218
	v_fma_f32 v97, v97, v203, v219
	v_fma_f32 v98, v98, v204, v220
	v_fma_f32 v99, v99, v205, v221
	v_cvt_pk_bf16_f32 v100, v100, v101
	v_cvt_pk_bf16_f32 v101, v102, v103
	v_cvt_pk_bf16_f32 v102, v96, v97
	v_cvt_pk_bf16_f32 v103, v98, v99
	global_store_dwordx4 v142, v[100:103], s[36:37] offset:64
	v_lshl_add_u32 v221, s12, 8, v158
	v_add_u32_e32 v221, 32, v221
	v_and_b32_e32 v218, 63, v221
	v_lshlrev_b32_e32 v218, 6, v218
	v_mov_b32_e32 v219, 0
	v_lshl_add_u64 v[214:215], v[138:139], 0, v[218:219]
	v_lshl_add_u64 v[216:217], v[140:141], 0, v[218:219]
	global_load_dwordx4 v[198:201], v[214:215], off
	global_load_dwordx4 v[202:205], v[214:215], off offset:16
	global_load_dwordx4 v[206:209], v[216:217], off
	global_load_dwordx4 v[210:213], v[216:217], off offset:16
	v_mul_f32_e32 v143, v93, v93
	v_mul_f32_e32 v144, v95, v95
	v_fmac_f32_e32 v143, v92, v92
	v_fmac_f32_e32 v144, v94, v94
	v_add_f32_e32 v142, v143, v144
	v_mul_f32_e32 v143, v89, v89
	v_mul_f32_e32 v144, v91, v91
	v_fmac_f32_e32 v143, v88, v88
	v_fmac_f32_e32 v144, v90, v90
	v_add_f32_e32 v143, v143, v144
	v_add_f32_e32 v142, v142, v143
	v_mul_f32_e32 v143, v85, v85
	v_mul_f32_e32 v144, v87, v87
	v_fmac_f32_e32 v143, v84, v84
	v_fmac_f32_e32 v144, v86, v86
	v_add_f32_e32 v143, v143, v144
	v_add_f32_e32 v142, v142, v143
	v_mul_f32_e32 v143, v81, v81
	v_mul_f32_e32 v144, v83, v83
	v_fmac_f32_e32 v143, v80, v80
	v_fmac_f32_e32 v144, v82, v82
	v_add_f32_e32 v143, v143, v144
	v_add_f32_e32 v142, v142, v143
	v_mov_b32_e32 v143, v142
	s_nop 1
	v_permlane16_swap_b32_e32 v142, v143
	v_add_f32_e32 v142, v142, v143
	v_mov_b32_e32 v143, v142
	s_nop 1
	v_permlane32_swap_b32_e32 v142, v143
	v_add_f32_e32 v142, v142, v143
	v_fmamk_f32 v144, v142, 0x3c800000, v153
	v_rsq_f32_e32 v144, v144
	s_nop 0
	v_mul_f32_e32 v92, v92, v144
	v_mul_f32_e32 v93, v93, v144
	v_mul_f32_e32 v94, v94, v144
	v_mul_f32_e32 v95, v95, v144
	v_mul_f32_e32 v92, v92, v162
	v_mul_f32_e32 v93, v93, v163
	v_mul_f32_e32 v94, v94, v164
	v_mul_f32_e32 v95, v95, v165
	v_mul_f32_e32 v88, v88, v144
	v_mul_f32_e32 v89, v89, v144
	v_mul_f32_e32 v90, v90, v144
	v_mul_f32_e32 v91, v91, v144
	v_mul_f32_e32 v88, v88, v166
	v_mul_f32_e32 v89, v89, v167
	v_mul_f32_e32 v90, v90, v168
	v_mul_f32_e32 v91, v91, v169
	v_mul_f32_e32 v84, v84, v144
	v_mul_f32_e32 v85, v85, v144
	v_mul_f32_e32 v86, v86, v144
	v_mul_f32_e32 v87, v87, v144
	v_mul_f32_e32 v84, v84, v170
	v_mul_f32_e32 v85, v85, v171
	v_mul_f32_e32 v86, v86, v172
	v_mul_f32_e32 v87, v87, v173
	v_mul_f32_e32 v80, v80, v144
	v_mul_f32_e32 v81, v81, v144
	v_mul_f32_e32 v82, v82, v144
	v_mul_f32_e32 v83, v83, v144
	v_mul_f32_e32 v80, v80, v174
	v_mul_f32_e32 v81, v81, v175
	v_mul_f32_e32 v82, v82, v176
	v_mul_f32_e32 v83, v83, v177
	ds_bpermute_b32 v214, v160, v92
	ds_bpermute_b32 v215, v160, v93
	ds_bpermute_b32 v216, v160, v94
	ds_bpermute_b32 v217, v160, v95
	ds_bpermute_b32 v218, v160, v88
	ds_bpermute_b32 v219, v160, v89
	ds_bpermute_b32 v220, v160, v90
	ds_bpermute_b32 v221, v160, v91
	s_waitcnt lgkmcnt(0)
	v_mul_f32_e32 v214, v186, v214
	v_mul_f32_e32 v215, v187, v215
	v_mul_f32_e32 v216, v188, v216
	v_mul_f32_e32 v217, v189, v217
	v_cndmask_b32_e64 v214, -v214, v214, s[6:7]
	v_cndmask_b32_e64 v215, -v215, v215, s[6:7]
	v_cndmask_b32_e64 v216, -v216, v216, s[6:7]
	v_cndmask_b32_e64 v217, -v217, v217, s[6:7]
	v_fma_f32 v92, v92, v178, v214
	v_fma_f32 v93, v93, v179, v215
	v_fma_f32 v94, v94, v180, v216
	v_fma_f32 v95, v95, v181, v217
	v_mul_f32_e32 v218, v190, v218
	v_mul_f32_e32 v219, v191, v219
	v_mul_f32_e32 v220, v192, v220
	v_mul_f32_e32 v221, v193, v221
	v_cndmask_b32_e64 v218, -v218, v218, s[6:7]
	v_cndmask_b32_e64 v219, -v219, v219, s[6:7]
	v_cndmask_b32_e64 v220, -v220, v220, s[6:7]
	v_cndmask_b32_e64 v221, -v221, v221, s[6:7]
	v_fma_f32 v88, v88, v182, v218
	v_fma_f32 v89, v89, v183, v219
	v_fma_f32 v90, v90, v184, v220
	v_fma_f32 v91, v91, v185, v221
	v_lshl_add_u32 v142, s12, 8, v158
	v_add_u32_e32 v142, 32, v142
	v_lshl_add_u32 v142, v142, s13, v154
	v_cvt_pk_bf16_f32 v92, v92, v93
	v_cvt_pk_bf16_f32 v93, v94, v95
	v_cvt_pk_bf16_f32 v94, v88, v89
	v_cvt_pk_bf16_f32 v95, v90, v91
	global_store_dwordx4 v142, v[92:95], s[36:37]
	ds_bpermute_b32 v214, v160, v84
	ds_bpermute_b32 v215, v160, v85
	ds_bpermute_b32 v216, v160, v86
	ds_bpermute_b32 v217, v160, v87
	ds_bpermute_b32 v218, v160, v80
	ds_bpermute_b32 v219, v160, v81
	ds_bpermute_b32 v220, v160, v82
	ds_bpermute_b32 v221, v160, v83
	s_waitcnt vmcnt(1)
	s_waitcnt lgkmcnt(0)
; __device__ __forceinline__ unsigned pkbf(float lo, float hi) { f32x2_t v = {lo, hi}; bf16x2_t b = __builtin_convertvector(v, bf16x2_t); return __builtin_bit_cast(unsigned, b); }
;     __device__ __forceinline__ void operator()(const f32x4 (&acc)[2][2][4][2], const pg8::Unit& u, int wr, int wc, int fr, int fq) const {
;     ...
;                 const int t = row & (SEQ - 1);
; #pragma unroll
;                 for (int bj = 0; bj < 2; ++bj) {
;                     f32x4 v0 = acc[ai][bj][m][0], v1 = acc[ai][bj][m][1];
;                     if (kind < 2) {
;                         v0 = v0 * rs * *(const f32x4*)(gp + 32 * bj); v1 = v1 * rs * *(const f32x4*)(gp + 32 * bj + 4);
;                         if (dorope) {
;                             const int pos = bj ? (t & 63) : (t >> 6);
;                             const f32x4 c0 = *(const f32x4*)(rp + pos * 16), c1 = *(const f32x4*)(rp + pos * 16 + 4);
;                             const f32x4 s0 = *(const f32x4*)(rp + 2048 + pos * 16), s1 = *(const f32x4*)(rp + 2048 + pos * 16 + 4);
;                             f32x4 o0, o1;
; #pragma unroll
;                             for (int i = 0; i < 4; ++i) { const float p0 = __uint_as_float((unsigned)__builtin_amdgcn_ds_bpermute(paddr, (int)__float_as_uint(v0[i]))) * s0[i], p1 = __uint_as_float((unsigned)__builtin_amdgcn_ds_bpermute(paddr, (int)__float_as_uint(v1[i]))) * s1[i];
;                                 o0[i] = v0[i] * c0[i] + (fq >= 2 ? p0 : -p0); o1[i] = v1[i] * c1[i] + (fq >= 2 ? p1 : -p1); }
;                             v0 = o0; v1 = o1;
;                         }
;                     }
;                     u32x4 w; w.x = pkbf(v0[0], v0[1]); w.y = pkbf(v0[2], v0[3]); w.z = pkbf(v1[0], v1[1]); w.w = pkbf(v1[2], v1[3]);
;                     *(u32x4*)(dst + (size_t)row * pitch + 32 * bj) = w;
	v_mul_f32_e32 v214, v206, v214
	v_mul_f32_e32 v215, v207, v215
	v_mul_f32_e32 v216, v208, v216
	v_mul_f32_e32 v217, v209, v217
	v_cndmask_b32_e64 v214, -v214, v214, s[6:7]
	v_cndmask_b32_e64 v215, -v215, v215, s[6:7]
	v_cndmask_b32_e64 v216, -v216, v216, s[6:7]
	v_cndmask_b32_e64 v217, -v217, v217, s[6:7]
	v_fma_f32 v84, v84, v198, v214
	v_fma_f32 v85, v85, v199, v215
	v_fma_f32 v86, v86, v200, v216
	v_fma_f32 v87, v87, v201, v217
	v_mul_f32_e32 v218, v210, v218
	v_mul_f32_e32 v219, v211, v219
	v_mul_f32_e32 v220, v212, v220
	v_mul_f32_e32 v221, v213, v221
	v_cndmask_b32_e64 v218, -v218, v218, s[6:7]
	v_cndmask_b32_e64 v219, -v219, v219, s[6:7]
	v_cndmask_b32_e64 v220, -v220, v220, s[6:7]
	v_cndmask_b32_e64 v221, -v221, v221, s[6:7]
	v_fma_f32 v80, v80, v202, v218
	v_fma_f32 v81, v81, v203, v219
	v_fma_f32 v82, v82, v204, v220
	v_fma_f32 v83, v83, v205, v221
	v_cvt_pk_bf16_f32 v84, v84, v85
	v_cvt_pk_bf16_f32 v85, v86, v87
	v_cvt_pk_bf16_f32 v86, v80, v81
	v_cvt_pk_bf16_f32 v87, v82, v83
	global_store_dwordx4 v142, v[84:87], s[36:37] offset:64
	v_lshl_add_u32 v221, s12, 8, v158
	v_add_u32_e32 v221, 48, v221
	v_and_b32_e32 v218, 63, v221
	v_lshlrev_b32_e32 v218, 6, v218
	v_mov_b32_e32 v219, 0
	v_lshl_add_u64 v[214:215], v[138:139], 0, v[218:219]
	v_lshl_add_u64 v[216:217], v[140:141], 0, v[218:219]
	global_load_dwordx4 v[198:201], v[214:215], off
	global_load_dwordx4 v[202:205], v[214:215], off offset:16
	global_load_dwordx4 v[206:209], v[216:217], off
	global_load_dwordx4 v[210:213], v[216:217], off offset:16
	v_mul_f32_e32 v143, v77, v77
	v_mul_f32_e32 v144, v79, v79
	v_fmac_f32_e32 v143, v76, v76
	v_fmac_f32_e32 v144, v78, v78
	v_add_f32_e32 v142, v143, v144
	v_mul_f32_e32 v143, v73, v73
	v_mul_f32_e32 v144, v75, v75
	v_fmac_f32_e32 v143, v72, v72
	v_fmac_f32_e32 v144, v74, v74
	v_add_f32_e32 v143, v143, v144
	v_add_f32_e32 v142, v142, v143
	v_mul_f32_e32 v143, v69, v69
	v_mul_f32_e32 v144, v71, v71
	v_fmac_f32_e32 v143, v68, v68
	v_fmac_f32_e32 v144, v70, v70
	v_add_f32_e32 v143, v143, v144
	v_add_f32_e32 v142, v142, v143
	v_mul_f32_e32 v143, v65, v65
	v_mul_f32_e32 v144, v67, v67
	v_fmac_f32_e32 v143, v64, v64
	v_fmac_f32_e32 v144, v66, v66
	v_add_f32_e32 v143, v143, v144
	v_add_f32_e32 v142, v142, v143
	v_mov_b32_e32 v143, v142
	s_nop 1
	v_permlane16_swap_b32_e32 v142, v143
	v_add_f32_e32 v142, v142, v143
	v_mov_b32_e32 v143, v142
	s_nop 1
	v_permlane32_swap_b32_e32 v142, v143
	v_add_f32_e32 v142, v142, v143
	v_fmamk_f32 v144, v142, 0x3c800000, v153
	v_rsq_f32_e32 v144, v144
	s_nop 0
	v_mul_f32_e32 v76, v76, v144
	v_mul_f32_e32 v77, v77, v144
	v_mul_f32_e32 v78, v78, v144
	v_mul_f32_e32 v79, v79, v144
	v_mul_f32_e32 v76, v76, v162
	v_mul_f32_e32 v77, v77, v163
	v_mul_f32_e32 v78, v78, v164
	v_mul_f32_e32 v79, v79, v165
	v_mul_f32_e32 v72, v72, v144
	v_mul_f32_e32 v73, v73, v144
	v_mul_f32_e32 v74, v74, v144
	v_mul_f32_e32 v75, v75, v144
	v_mul_f32_e32 v72, v72, v166
	v_mul_f32_e32 v73, v73, v167
	v_mul_f32_e32 v74, v74, v168
	v_mul_f32_e32 v75, v75, v169
	v_mul_f32_e32 v68, v68, v144
	v_mul_f32_e32 v69, v69, v144
	v_mul_f32_e32 v70, v70, v144
	v_mul_f32_e32 v71, v71, v144
	v_mul_f32_e32 v68, v68, v170
	v_mul_f32_e32 v69, v69, v171
	v_mul_f32_e32 v70, v70, v172
	v_mul_f32_e32 v71, v71, v173
	v_mul_f32_e32 v64, v64, v144
	v_mul_f32_e32 v65, v65, v144
	v_mul_f32_e32 v66, v66, v144
	v_mul_f32_e32 v67, v67, v144
	v_mul_f32_e32 v64, v64, v174
	v_mul_f32_e32 v65, v65, v175
	v_mul_f32_e32 v66, v66, v176
	v_mul_f32_e32 v67, v67, v177
	ds_bpermute_b32 v214, v160, v76
	ds_bpermute_b32 v215, v160, v77
	ds_bpermute_b32 v216, v160, v78
	ds_bpermute_b32 v217, v160, v79
	ds_bpermute_b32 v218, v160, v72
	ds_bpermute_b32 v219, v160, v73
	ds_bpermute_b32 v220, v160, v74
	ds_bpermute_b32 v221, v160, v75
	s_waitcnt lgkmcnt(0)
	v_mul_f32_e32 v214, v186, v214
	v_mul_f32_e32 v215, v187, v215
	v_mul_f32_e32 v216, v188, v216
	v_mul_f32_e32 v217, v189, v217
	v_cndmask_b32_e64 v214, -v214, v214, s[6:7]
	v_cndmask_b32_e64 v215, -v215, v215, s[6:7]
	v_cndmask_b32_e64 v216, -v216, v216, s[6:7]
	v_cndmask_b32_e64 v217, -v217, v217, s[6:7]
	v_fma_f32 v76, v76, v178, v214
	v_fma_f32 v77, v77, v179, v215
	v_fma_f32 v78, v78, v180, v216
	v_fma_f32 v79, v79, v181, v217
	v_mul_f32_e32 v218, v190, v218
	v_mul_f32_e32 v219, v191, v219
	v_mul_f32_e32 v220, v192, v220
	v_mul_f32_e32 v221, v193, v221
	v_cndmask_b32_e64 v218, -v218, v218, s[6:7]
	v_cndmask_b32_e64 v219, -v219, v219, s[6:7]
	v_cndmask_b32_e64 v220, -v220, v220, s[6:7]
	v_cndmask_b32_e64 v221, -v221, v221, s[6:7]
	v_fma_f32 v72, v72, v182, v218
	v_fma_f32 v73, v73, v183, v219
	v_fma_f32 v74, v74, v184, v220
	v_fma_f32 v75, v75, v185, v221
	v_lshl_add_u32 v142, s12, 8, v158
	v_add_u32_e32 v142, 48, v142
	v_lshl_add_u32 v142, v142, s13, v154
	v_cvt_pk_bf16_f32 v76, v76, v77
	v_cvt_pk_bf16_f32 v77, v78, v79
	v_cvt_pk_bf16_f32 v78, v72, v73
	v_cvt_pk_bf16_f32 v79, v74, v75
	global_store_dwordx4 v142, v[76:79], s[36:37]
	ds_bpermute_b32 v214, v160, v68
	ds_bpermute_b32 v215, v160, v69
	ds_bpermute_b32 v216, v160, v70
	ds_bpermute_b32 v217, v160, v71
	ds_bpermute_b32 v218, v160, v64
	ds_bpermute_b32 v219, v160, v65
	ds_bpermute_b32 v220, v160, v66
	ds_bpermute_b32 v221, v160, v67
	s_waitcnt vmcnt(1)
	s_waitcnt lgkmcnt(0)
; __device__ __forceinline__ unsigned pkbf(float lo, float hi) { f32x2_t v = {lo, hi}; bf16x2_t b = __builtin_convertvector(v, bf16x2_t); return __builtin_bit_cast(unsigned, b); }
;     __device__ __forceinline__ void operator()(const f32x4 (&acc)[2][2][4][2], const pg8::Unit& u, int wr, int wc, int fr, int fq) const {
;     ...
;                 const int t = row & (SEQ - 1);
; #pragma unroll
;                 for (int bj = 0; bj < 2; ++bj) {
;                     f32x4 v0 = acc[ai][bj][m][0], v1 = acc[ai][bj][m][1];
;                     if (kind < 2) {
;                         v0 = v0 * rs * *(const f32x4*)(gp + 32 * bj); v1 = v1 * rs * *(const f32x4*)(gp + 32 * bj + 4);
;                         if (dorope) {
;                             const int pos = bj ? (t & 63) : (t >> 6);
;                             const f32x4 c0 = *(const f32x4*)(rp + pos * 16), c1 = *(const f32x4*)(rp + pos * 16 + 4);
;                             const f32x4 s0 = *(const f32x4*)(rp + 2048 + pos * 16), s1 = *(const f32x4*)(rp + 2048 + pos * 16 + 4);
;                             f32x4 o0, o1;
; #pragma unroll
;                             for (int i = 0; i < 4; ++i) { const float p0 = __uint_as_float((unsigned)__builtin_amdgcn_ds_bpermute(paddr, (int)__float_as_uint(v0[i]))) * s0[i], p1 = __uint_as_float((unsigned)__builtin_amdgcn_ds_bpermute(paddr, (int)__float_as_uint(v1[i]))) * s1[i];
;                                 o0[i] = v0[i] * c0[i] + (fq >= 2 ? p0 : -p0); o1[i] = v1[i] * c1[i] + (fq >= 2 ? p1 : -p1); }
;                             v0 = o0; v1 = o1;
;                         }
;                     }
;                     u32x4 w; w.x = pkbf(v0[0], v0[1]); w.y = pkbf(v0[2], v0[3]); w.z = pkbf(v1[0], v1[1]); w.w = pkbf(v1[2], v1[3]);
;                     *(u32x4*)(dst + (size_t)row * pitch + 32 * bj) = w;
	v_mul_f32_e32 v214, v206, v214
	v_mul_f32_e32 v215, v207, v215
	v_mul_f32_e32 v216, v208, v216
	v_mul_f32_e32 v217, v209, v217
	v_cndmask_b32_e64 v214, -v214, v214, s[6:7]
	v_cndmask_b32_e64 v215, -v215, v215, s[6:7]
	v_cndmask_b32_e64 v216, -v216, v216, s[6:7]
	v_cndmask_b32_e64 v217, -v217, v217, s[6:7]
	v_fma_f32 v68, v68, v198, v214
	v_fma_f32 v69, v69, v199, v215
	v_fma_f32 v70, v70, v200, v216
	v_fma_f32 v71, v71, v201, v217
	v_mul_f32_e32 v218, v210, v218
	v_mul_f32_e32 v219, v211, v219
	v_mul_f32_e32 v220, v212, v220
	v_mul_f32_e32 v221, v213, v221
	v_cndmask_b32_e64 v218, -v218, v218, s[6:7]
	v_cndmask_b32_e64 v219, -v219, v219, s[6:7]
	v_cndmask_b32_e64 v220, -v220, v220, s[6:7]
	v_cndmask_b32_e64 v221, -v221, v221, s[6:7]
	v_fma_f32 v64, v64, v202, v218
	v_fma_f32 v65, v65, v203, v219
	v_fma_f32 v66, v66, v204, v220
	v_fma_f32 v67, v67, v205, v221
	v_cvt_pk_bf16_f32 v68, v68, v69
	v_cvt_pk_bf16_f32 v69, v70, v71
	v_cvt_pk_bf16_f32 v70, v64, v65
	v_cvt_pk_bf16_f32 v71, v66, v67
	global_store_dwordx4 v142, v[68:71], s[36:37] offset:64
	v_lshl_add_u32 v221, s12, 8, v158
	v_add_u32_e32 v221, 128, v221
	v_and_b32_e32 v218, 0x1fc0, v221
	v_mov_b32_e32 v219, 0
	v_lshl_add_u64 v[214:215], v[138:139], 0, v[218:219]
	v_lshl_add_u64 v[216:217], v[140:141], 0, v[218:219]
	global_load_dwordx4 v[178:181], v[214:215], off
	global_load_dwordx4 v[182:185], v[214:215], off offset:16
	global_load_dwordx4 v[186:189], v[216:217], off
	global_load_dwordx4 v[190:193], v[216:217], off offset:16
	v_and_b32_e32 v218, 63, v221
	v_lshlrev_b32_e32 v218, 6, v218
	v_mov_b32_e32 v219, 0
	v_lshl_add_u64 v[214:215], v[138:139], 0, v[218:219]
	v_lshl_add_u64 v[216:217], v[140:141], 0, v[218:219]
	global_load_dwordx4 v[198:201], v[214:215], off
	global_load_dwordx4 v[202:205], v[214:215], off offset:16
	global_load_dwordx4 v[206:209], v[216:217], off
	global_load_dwordx4 v[210:213], v[216:217], off offset:16
	v_mul_f32_e32 v143, v61, v61
	v_mul_f32_e32 v144, v63, v63
	v_fmac_f32_e32 v143, v60, v60
	v_fmac_f32_e32 v144, v62, v62
	v_add_f32_e32 v142, v143, v144
	v_mul_f32_e32 v143, v57, v57
	v_mul_f32_e32 v144, v59, v59
	v_fmac_f32_e32 v143, v56, v56
	v_fmac_f32_e32 v144, v58, v58
	v_add_f32_e32 v143, v143, v144
	v_add_f32_e32 v142, v142, v143
	v_mul_f32_e32 v143, v53, v53
	v_mul_f32_e32 v144, v55, v55
	v_fmac_f32_e32 v143, v52, v52
	v_fmac_f32_e32 v144, v54, v54
	v_add_f32_e32 v143, v143, v144
	v_add_f32_e32 v142, v142, v143
	v_mul_f32_e32 v143, v49, v49
	v_mul_f32_e32 v144, v51, v51
	v_fmac_f32_e32 v143, v48, v48
	v_fmac_f32_e32 v144, v50, v50
	v_add_f32_e32 v143, v143, v144
	v_add_f32_e32 v142, v142, v143
	v_mov_b32_e32 v143, v142
	s_nop 1
	v_permlane16_swap_b32_e32 v142, v143
	v_add_f32_e32 v142, v142, v143
	v_mov_b32_e32 v143, v142
	s_nop 1
	v_permlane32_swap_b32_e32 v142, v143
	v_add_f32_e32 v142, v142, v143
	v_fmamk_f32 v144, v142, 0x3c800000, v153
	v_rsq_f32_e32 v144, v144
	s_nop 0
	v_mul_f32_e32 v60, v60, v144
	v_mul_f32_e32 v61, v61, v144
	v_mul_f32_e32 v62, v62, v144
	v_mul_f32_e32 v63, v63, v144
	v_mul_f32_e32 v60, v60, v162
	v_mul_f32_e32 v61, v61, v163
	v_mul_f32_e32 v62, v62, v164
	v_mul_f32_e32 v63, v63, v165
	v_mul_f32_e32 v56, v56, v144
	v_mul_f32_e32 v57, v57, v144
	v_mul_f32_e32 v58, v58, v144
	v_mul_f32_e32 v59, v59, v144
	v_mul_f32_e32 v56, v56, v166
	v_mul_f32_e32 v57, v57, v167
	v_mul_f32_e32 v58, v58, v168
	v_mul_f32_e32 v59, v59, v169
	v_mul_f32_e32 v52, v52, v144
	v_mul_f32_e32 v53, v53, v144
	v_mul_f32_e32 v54, v54, v144
	v_mul_f32_e32 v55, v55, v144
	v_mul_f32_e32 v52, v52, v170
	v_mul_f32_e32 v53, v53, v171
	v_mul_f32_e32 v54, v54, v172
	v_mul_f32_e32 v55, v55, v173
	v_mul_f32_e32 v48, v48, v144
	v_mul_f32_e32 v49, v49, v144
	v_mul_f32_e32 v50, v50, v144
	v_mul_f32_e32 v51, v51, v144
	v_mul_f32_e32 v48, v48, v174
	v_mul_f32_e32 v49, v49, v175
	v_mul_f32_e32 v50, v50, v176
	v_mul_f32_e32 v51, v51, v177
	ds_bpermute_b32 v214, v160, v60
	ds_bpermute_b32 v215, v160, v61
	ds_bpermute_b32 v216, v160, v62
	ds_bpermute_b32 v217, v160, v63
	ds_bpermute_b32 v218, v160, v56
	ds_bpermute_b32 v219, v160, v57
	ds_bpermute_b32 v220, v160, v58
	ds_bpermute_b32 v221, v160, v59
	s_waitcnt vmcnt(4)
	s_waitcnt lgkmcnt(0)
	v_mul_f32_e32 v214, v186, v214
	v_mul_f32_e32 v215, v187, v215
	v_mul_f32_e32 v216, v188, v216
	v_mul_f32_e32 v217, v189, v217
	v_cndmask_b32_e64 v214, -v214, v214, s[6:7]
	v_cndmask_b32_e64 v215, -v215, v215, s[6:7]
	v_cndmask_b32_e64 v216, -v216, v216, s[6:7]
	v_cndmask_b32_e64 v217, -v217, v217, s[6:7]
	v_fma_f32 v60, v60, v178, v214
	v_fma_f32 v61, v61, v179, v215
	v_fma_f32 v62, v62, v180, v216
	v_fma_f32 v63, v63, v181, v217
	v_mul_f32_e32 v218, v190, v218
	v_mul_f32_e32 v219, v191, v219
	v_mul_f32_e32 v220, v192, v220
	v_mul_f32_e32 v221, v193, v221
	v_cndmask_b32_e64 v218, -v218, v218, s[6:7]
	v_cndmask_b32_e64 v219, -v219, v219, s[6:7]
	v_cndmask_b32_e64 v220, -v220, v220, s[6:7]
	v_cndmask_b32_e64 v221, -v221, v221, s[6:7]
	v_fma_f32 v56, v56, v182, v218
	v_fma_f32 v57, v57, v183, v219
	v_fma_f32 v58, v58, v184, v220
	v_fma_f32 v59, v59, v185, v221
	v_lshl_add_u32 v142, s12, 8, v158
	v_add_u32_e32 v142, 128, v142
	v_lshl_add_u32 v142, v142, s13, v154
	v_cvt_pk_bf16_f32 v60, v60, v61
	v_cvt_pk_bf16_f32 v61, v62, v63
	v_cvt_pk_bf16_f32 v62, v56, v57
	v_cvt_pk_bf16_f32 v63, v58, v59
	global_store_dwordx4 v142, v[60:63], s[36:37]
	ds_bpermute_b32 v214, v160, v52
	ds_bpermute_b32 v215, v160, v53
	ds_bpermute_b32 v216, v160, v54
	ds_bpermute_b32 v217, v160, v55
	ds_bpermute_b32 v218, v160, v48
	ds_bpermute_b32 v219, v160, v49
	ds_bpermute_b32 v220, v160, v50
	ds_bpermute_b32 v221, v160, v51
	s_waitcnt vmcnt(1)
	s_waitcnt lgkmcnt(0)
; __device__ __forceinline__ unsigned pkbf(float lo, float hi) { f32x2_t v = {lo, hi}; bf16x2_t b = __builtin_convertvector(v, bf16x2_t); return __builtin_bit_cast(unsigned, b); }
;     __device__ __forceinline__ void operator()(const f32x4 (&acc)[2][2][4][2], const pg8::Unit& u, int wr, int wc, int fr, int fq) const {
;     ...
;                 const int t = row & (SEQ - 1);
; #pragma unroll
;                 for (int bj = 0; bj < 2; ++bj) {
;                     f32x4 v0 = acc[ai][bj][m][0], v1 = acc[ai][bj][m][1];
;                     if (kind < 2) {
;                         v0 = v0 * rs * *(const f32x4*)(gp + 32 * bj); v1 = v1 * rs * *(const f32x4*)(gp + 32 * bj + 4);
;                         if (dorope) {
;                             const int pos = bj ? (t & 63) : (t >> 6);
;                             const f32x4 c0 = *(const f32x4*)(rp + pos * 16), c1 = *(const f32x4*)(rp + pos * 16 + 4);
;                             const f32x4 s0 = *(const f32x4*)(rp + 2048 + pos * 16), s1 = *(const f32x4*)(rp + 2048 + pos * 16 + 4);
;                             f32x4 o0, o1;
; #pragma unroll
;                             for (int i = 0; i < 4; ++i) { const float p0 = __uint_as_float((unsigned)__builtin_amdgcn_ds_bpermute(paddr, (int)__float_as_uint(v0[i]))) * s0[i], p1 = __uint_as_float((unsigned)__builtin_amdgcn_ds_bpermute(paddr, (int)__float_as_uint(v1[i]))) * s1[i];
;                                 o0[i] = v0[i] * c0[i] + (fq >= 2 ? p0 : -p0); o1[i] = v1[i] * c1[i] + (fq >= 2 ? p1 : -p1); }
;                             v0 = o0; v1 = o1;
;                         }
;                     }
;                     u32x4 w; w.x = pkbf(v0[0], v0[1]); w.y = pkbf(v0[2], v0[3]); w.z = pkbf(v1[0], v1[1]); w.w = pkbf(v1[2], v1[3]);
;                     *(u32x4*)(dst + (size_t)row * pitch + 32 * bj) = w;
	v_mul_f32_e32 v214, v206, v214
	v_mul_f32_e32 v215, v207, v215
	v_mul_f32_e32 v216, v208, v216
	v_mul_f32_e32 v217, v209, v217
	v_cndmask_b32_e64 v214, -v214, v214, s[6:7]
	v_cndmask_b32_e64 v215, -v215, v215, s[6:7]
	v_cndmask_b32_e64 v216, -v216, v216, s[6:7]
	v_cndmask_b32_e64 v217, -v217, v217, s[6:7]
	v_fma_f32 v52, v52, v198, v214
	v_fma_f32 v53, v53, v199, v215
	v_fma_f32 v54, v54, v200, v216
	v_fma_f32 v55, v55, v201, v217
	v_mul_f32_e32 v218, v210, v218
	v_mul_f32_e32 v219, v211, v219
	v_mul_f32_e32 v220, v212, v220
	v_mul_f32_e32 v221, v213, v221
	v_cndmask_b32_e64 v218, -v218, v218, s[6:7]
	v_cndmask_b32_e64 v219, -v219, v219, s[6:7]
	v_cndmask_b32_e64 v220, -v220, v220, s[6:7]
	v_cndmask_b32_e64 v221, -v221, v221, s[6:7]
	v_fma_f32 v48, v48, v202, v218
	v_fma_f32 v49, v49, v203, v219
	v_fma_f32 v50, v50, v204, v220
	v_fma_f32 v51, v51, v205, v221
	v_cvt_pk_bf16_f32 v52, v52, v53
	v_cvt_pk_bf16_f32 v53, v54, v55
	v_cvt_pk_bf16_f32 v54, v48, v49
	v_cvt_pk_bf16_f32 v55, v50, v51
	global_store_dwordx4 v142, v[52:55], s[36:37] offset:64
	v_lshl_add_u32 v221, s12, 8, v158
	v_add_u32_e32 v221, 144, v221
	v_and_b32_e32 v218, 63, v221
	v_lshlrev_b32_e32 v218, 6, v218
	v_mov_b32_e32 v219, 0
	v_lshl_add_u64 v[214:215], v[138:139], 0, v[218:219]
	v_lshl_add_u64 v[216:217], v[140:141], 0, v[218:219]
	global_load_dwordx4 v[198:201], v[214:215], off
	global_load_dwordx4 v[202:205], v[214:215], off offset:16
	global_load_dwordx4 v[206:209], v[216:217], off
	global_load_dwordx4 v[210:213], v[216:217], off offset:16
	v_mul_f32_e32 v143, v45, v45
	v_mul_f32_e32 v144, v47, v47
	v_fmac_f32_e32 v143, v44, v44
	v_fmac_f32_e32 v144, v46, v46
	v_add_f32_e32 v142, v143, v144
	v_mul_f32_e32 v143, v41, v41
	v_mul_f32_e32 v144, v43, v43
	v_fmac_f32_e32 v143, v40, v40
	v_fmac_f32_e32 v144, v42, v42
	v_add_f32_e32 v143, v143, v144
	v_add_f32_e32 v142, v142, v143
	v_mul_f32_e32 v143, v37, v37
	v_mul_f32_e32 v144, v39, v39
	v_fmac_f32_e32 v143, v36, v36
	v_fmac_f32_e32 v144, v38, v38
	v_add_f32_e32 v143, v143, v144
	v_add_f32_e32 v142, v142, v143
	v_mul_f32_e32 v143, v33, v33
	v_mul_f32_e32 v144, v35, v35
	v_fmac_f32_e32 v143, v32, v32
	v_fmac_f32_e32 v144, v34, v34
	v_add_f32_e32 v143, v143, v144
	v_add_f32_e32 v142, v142, v143
	v_mov_b32_e32 v143, v142
	s_nop 1
	v_permlane16_swap_b32_e32 v142, v143
	v_add_f32_e32 v142, v142, v143
	v_mov_b32_e32 v143, v142
	s_nop 1
	v_permlane32_swap_b32_e32 v142, v143
	v_add_f32_e32 v142, v142, v143
	v_fmamk_f32 v144, v142, 0x3c800000, v153
	v_rsq_f32_e32 v144, v144
	s_nop 0
	v_mul_f32_e32 v44, v44, v144
	v_mul_f32_e32 v45, v45, v144
	v_mul_f32_e32 v46, v46, v144
	v_mul_f32_e32 v47, v47, v144
	v_mul_f32_e32 v44, v44, v162
	v_mul_f32_e32 v45, v45, v163
	v_mul_f32_e32 v46, v46, v164
	v_mul_f32_e32 v47, v47, v165
	v_mul_f32_e32 v40, v40, v144
	v_mul_f32_e32 v41, v41, v144
	v_mul_f32_e32 v42, v42, v144
	v_mul_f32_e32 v43, v43, v144
	v_mul_f32_e32 v40, v40, v166
	v_mul_f32_e32 v41, v41, v167
	v_mul_f32_e32 v42, v42, v168
	v_mul_f32_e32 v43, v43, v169
	v_mul_f32_e32 v36, v36, v144
	v_mul_f32_e32 v37, v37, v144
	v_mul_f32_e32 v38, v38, v144
	v_mul_f32_e32 v39, v39, v144
	v_mul_f32_e32 v36, v36, v170
	v_mul_f32_e32 v37, v37, v171
	v_mul_f32_e32 v38, v38, v172
	v_mul_f32_e32 v39, v39, v173
	v_mul_f32_e32 v32, v32, v144
	v_mul_f32_e32 v33, v33, v144
	v_mul_f32_e32 v34, v34, v144
	v_mul_f32_e32 v35, v35, v144
	v_mul_f32_e32 v32, v32, v174
	v_mul_f32_e32 v33, v33, v175
	v_mul_f32_e32 v34, v34, v176
	v_mul_f32_e32 v35, v35, v177
	ds_bpermute_b32 v214, v160, v44
	ds_bpermute_b32 v215, v160, v45
	ds_bpermute_b32 v216, v160, v46
	ds_bpermute_b32 v217, v160, v47
	ds_bpermute_b32 v218, v160, v40
	ds_bpermute_b32 v219, v160, v41
	ds_bpermute_b32 v220, v160, v42
	ds_bpermute_b32 v221, v160, v43
	s_waitcnt lgkmcnt(0)
	v_mul_f32_e32 v214, v186, v214
	v_mul_f32_e32 v215, v187, v215
	v_mul_f32_e32 v216, v188, v216
	v_mul_f32_e32 v217, v189, v217
	v_cndmask_b32_e64 v214, -v214, v214, s[6:7]
	v_cndmask_b32_e64 v215, -v215, v215, s[6:7]
	v_cndmask_b32_e64 v216, -v216, v216, s[6:7]
	v_cndmask_b32_e64 v217, -v217, v217, s[6:7]
	v_fma_f32 v44, v44, v178, v214
	v_fma_f32 v45, v45, v179, v215
	v_fma_f32 v46, v46, v180, v216
	v_fma_f32 v47, v47, v181, v217
	v_mul_f32_e32 v218, v190, v218
	v_mul_f32_e32 v219, v191, v219
	v_mul_f32_e32 v220, v192, v220
	v_mul_f32_e32 v221, v193, v221
	v_cndmask_b32_e64 v218, -v218, v218, s[6:7]
	v_cndmask_b32_e64 v219, -v219, v219, s[6:7]
	v_cndmask_b32_e64 v220, -v220, v220, s[6:7]
	v_cndmask_b32_e64 v221, -v221, v221, s[6:7]
	v_fma_f32 v40, v40, v182, v218
	v_fma_f32 v41, v41, v183, v219
	v_fma_f32 v42, v42, v184, v220
	v_fma_f32 v43, v43, v185, v221
	v_lshl_add_u32 v142, s12, 8, v158
	v_add_u32_e32 v142, 144, v142
	v_lshl_add_u32 v142, v142, s13, v154
	v_cvt_pk_bf16_f32 v44, v44, v45
	v_cvt_pk_bf16_f32 v45, v46, v47
	v_cvt_pk_bf16_f32 v46, v40, v41
	v_cvt_pk_bf16_f32 v47, v42, v43
	global_store_dwordx4 v142, v[44:47], s[36:37]
	ds_bpermute_b32 v214, v160, v36
	ds_bpermute_b32 v215, v160, v37
	ds_bpermute_b32 v216, v160, v38
	ds_bpermute_b32 v217, v160, v39
	ds_bpermute_b32 v218, v160, v32
	ds_bpermute_b32 v219, v160, v33
	ds_bpermute_b32 v220, v160, v34
	ds_bpermute_b32 v221, v160, v35
	s_waitcnt vmcnt(1)
	s_waitcnt lgkmcnt(0)
; __device__ __forceinline__ unsigned pkbf(float lo, float hi) { f32x2_t v = {lo, hi}; bf16x2_t b = __builtin_convertvector(v, bf16x2_t); return __builtin_bit_cast(unsigned, b); }
;     __device__ __forceinline__ void operator()(const f32x4 (&acc)[2][2][4][2], const pg8::Unit& u, int wr, int wc, int fr, int fq) const {
;     ...
;                 const int t = row & (SEQ - 1);
; #pragma unroll
;                 for (int bj = 0; bj < 2; ++bj) {
;                     f32x4 v0 = acc[ai][bj][m][0], v1 = acc[ai][bj][m][1];
;                     if (kind < 2) {
;                         v0 = v0 * rs * *(const f32x4*)(gp + 32 * bj); v1 = v1 * rs * *(const f32x4*)(gp + 32 * bj + 4);
;                         if (dorope) {
;                             const int pos = bj ? (t & 63) : (t >> 6);
;                             const f32x4 c0 = *(const f32x4*)(rp + pos * 16), c1 = *(const f32x4*)(rp + pos * 16 + 4);
;                             const f32x4 s0 = *(const f32x4*)(rp + 2048 + pos * 16), s1 = *(const f32x4*)(rp + 2048 + pos * 16 + 4);
;                             f32x4 o0, o1;
; #pragma unroll
;                             for (int i = 0; i < 4; ++i) { const float p0 = __uint_as_float((unsigned)__builtin_amdgcn_ds_bpermute(paddr, (int)__float_as_uint(v0[i]))) * s0[i], p1 = __uint_as_float((unsigned)__builtin_amdgcn_ds_bpermute(paddr, (int)__float_as_uint(v1[i]))) * s1[i];
;                                 o0[i] = v0[i] * c0[i] + (fq >= 2 ? p0 : -p0); o1[i] = v1[i] * c1[i] + (fq >= 2 ? p1 : -p1); }
;                             v0 = o0; v1 = o1;
;                         }
;                     }
;                     u32x4 w; w.x = pkbf(v0[0], v0[1]); w.y = pkbf(v0[2], v0[3]); w.z = pkbf(v1[0], v1[1]); w.w = pkbf(v1[2], v1[3]);
;                     *(u32x4*)(dst + (size_t)row * pitch + 32 * bj) = w;
	v_mul_f32_e32 v214, v206, v214
	v_mul_f32_e32 v215, v207, v215
	v_mul_f32_e32 v216, v208, v216
	v_mul_f32_e32 v217, v209, v217
	v_cndmask_b32_e64 v214, -v214, v214, s[6:7]
	v_cndmask_b32_e64 v215, -v215, v215, s[6:7]
	v_cndmask_b32_e64 v216, -v216, v216, s[6:7]
	v_cndmask_b32_e64 v217, -v217, v217, s[6:7]
	v_fma_f32 v36, v36, v198, v214
	v_fma_f32 v37, v37, v199, v215
	v_fma_f32 v38, v38, v200, v216
	v_fma_f32 v39, v39, v201, v217
	v_mul_f32_e32 v218, v210, v218
	v_mul_f32_e32 v219, v211, v219
	v_mul_f32_e32 v220, v212, v220
	v_mul_f32_e32 v221, v213, v221
	v_cndmask_b32_e64 v218, -v218, v218, s[6:7]
	v_cndmask_b32_e64 v219, -v219, v219, s[6:7]
	v_cndmask_b32_e64 v220, -v220, v220, s[6:7]
	v_cndmask_b32_e64 v221, -v221, v221, s[6:7]
	v_fma_f32 v32, v32, v202, v218
	v_fma_f32 v33, v33, v203, v219
	v_fma_f32 v34, v34, v204, v220
	v_fma_f32 v35, v35, v205, v221
	v_cvt_pk_bf16_f32 v36, v36, v37
	v_cvt_pk_bf16_f32 v37, v38, v39
	v_cvt_pk_bf16_f32 v38, v32, v33
	v_cvt_pk_bf16_f32 v39, v34, v35
	global_store_dwordx4 v142, v[36:39], s[36:37] offset:64
	v_lshl_add_u32 v221, s12, 8, v158
	v_add_u32_e32 v221, 160, v221
	v_and_b32_e32 v218, 63, v221
	v_lshlrev_b32_e32 v218, 6, v218
	v_mov_b32_e32 v219, 0
	v_lshl_add_u64 v[214:215], v[138:139], 0, v[218:219]
	v_lshl_add_u64 v[216:217], v[140:141], 0, v[218:219]
	global_load_dwordx4 v[198:201], v[214:215], off
	global_load_dwordx4 v[202:205], v[214:215], off offset:16
	global_load_dwordx4 v[206:209], v[216:217], off
	global_load_dwordx4 v[210:213], v[216:217], off offset:16
	v_mul_f32_e32 v143, v29, v29
	v_mul_f32_e32 v144, v31, v31
	v_fmac_f32_e32 v143, v28, v28
	v_fmac_f32_e32 v144, v30, v30
	v_add_f32_e32 v142, v143, v144
	v_mul_f32_e32 v143, v25, v25
	v_mul_f32_e32 v144, v27, v27
	v_fmac_f32_e32 v143, v24, v24
	v_fmac_f32_e32 v144, v26, v26
	v_add_f32_e32 v143, v143, v144
	v_add_f32_e32 v142, v142, v143
	v_mul_f32_e32 v143, v21, v21
	v_mul_f32_e32 v144, v23, v23
	v_fmac_f32_e32 v143, v20, v20
	v_fmac_f32_e32 v144, v22, v22
	v_add_f32_e32 v143, v143, v144
	v_add_f32_e32 v142, v142, v143
	v_mul_f32_e32 v143, v17, v17
	v_mul_f32_e32 v144, v19, v19
	v_fmac_f32_e32 v143, v16, v16
	v_fmac_f32_e32 v144, v18, v18
	v_add_f32_e32 v143, v143, v144
	v_add_f32_e32 v142, v142, v143
	v_mov_b32_e32 v143, v142
	s_nop 1
	v_permlane16_swap_b32_e32 v142, v143
	v_add_f32_e32 v142, v142, v143
	v_mov_b32_e32 v143, v142
	s_nop 1
	v_permlane32_swap_b32_e32 v142, v143
	v_add_f32_e32 v142, v142, v143
	v_fmamk_f32 v144, v142, 0x3c800000, v153
	v_rsq_f32_e32 v144, v144
	s_nop 0
	v_mul_f32_e32 v28, v28, v144
	v_mul_f32_e32 v29, v29, v144
	v_mul_f32_e32 v30, v30, v144
	v_mul_f32_e32 v31, v31, v144
	v_mul_f32_e32 v28, v28, v162
	v_mul_f32_e32 v29, v29, v163
	v_mul_f32_e32 v30, v30, v164
	v_mul_f32_e32 v31, v31, v165
	v_mul_f32_e32 v24, v24, v144
	v_mul_f32_e32 v25, v25, v144
	v_mul_f32_e32 v26, v26, v144
	v_mul_f32_e32 v27, v27, v144
	v_mul_f32_e32 v24, v24, v166
	v_mul_f32_e32 v25, v25, v167
	v_mul_f32_e32 v26, v26, v168
	v_mul_f32_e32 v27, v27, v169
	v_mul_f32_e32 v20, v20, v144
	v_mul_f32_e32 v21, v21, v144
	v_mul_f32_e32 v22, v22, v144
	v_mul_f32_e32 v23, v23, v144
	v_mul_f32_e32 v20, v20, v170
	v_mul_f32_e32 v21, v21, v171
	v_mul_f32_e32 v22, v22, v172
	v_mul_f32_e32 v23, v23, v173
	v_mul_f32_e32 v16, v16, v144
	v_mul_f32_e32 v17, v17, v144
	v_mul_f32_e32 v18, v18, v144
	v_mul_f32_e32 v19, v19, v144
	v_mul_f32_e32 v16, v16, v174
	v_mul_f32_e32 v17, v17, v175
	v_mul_f32_e32 v18, v18, v176
	v_mul_f32_e32 v19, v19, v177
	ds_bpermute_b32 v214, v160, v28
	ds_bpermute_b32 v215, v160, v29
	ds_bpermute_b32 v216, v160, v30
	ds_bpermute_b32 v217, v160, v31
	ds_bpermute_b32 v218, v160, v24
	ds_bpermute_b32 v219, v160, v25
	ds_bpermute_b32 v220, v160, v26
	ds_bpermute_b32 v221, v160, v27
	s_waitcnt lgkmcnt(0)
	v_mul_f32_e32 v214, v186, v214
	v_mul_f32_e32 v215, v187, v215
	v_mul_f32_e32 v216, v188, v216
	v_mul_f32_e32 v217, v189, v217
	v_cndmask_b32_e64 v214, -v214, v214, s[6:7]
	v_cndmask_b32_e64 v215, -v215, v215, s[6:7]
	v_cndmask_b32_e64 v216, -v216, v216, s[6:7]
	v_cndmask_b32_e64 v217, -v217, v217, s[6:7]
	v_fma_f32 v28, v28, v178, v214
	v_fma_f32 v29, v29, v179, v215
	v_fma_f32 v30, v30, v180, v216
	v_fma_f32 v31, v31, v181, v217
	v_mul_f32_e32 v218, v190, v218
	v_mul_f32_e32 v219, v191, v219
	v_mul_f32_e32 v220, v192, v220
	v_mul_f32_e32 v221, v193, v221
	v_cndmask_b32_e64 v218, -v218, v218, s[6:7]
	v_cndmask_b32_e64 v219, -v219, v219, s[6:7]
	v_cndmask_b32_e64 v220, -v220, v220, s[6:7]
	v_cndmask_b32_e64 v221, -v221, v221, s[6:7]
	v_fma_f32 v24, v24, v182, v218
	v_fma_f32 v25, v25, v183, v219
	v_fma_f32 v26, v26, v184, v220
	v_fma_f32 v27, v27, v185, v221
	v_lshl_add_u32 v142, s12, 8, v158
	v_add_u32_e32 v142, 160, v142
	v_lshl_add_u32 v142, v142, s13, v154
	v_cvt_pk_bf16_f32 v28, v28, v29
	v_cvt_pk_bf16_f32 v29, v30, v31
	v_cvt_pk_bf16_f32 v30, v24, v25
	v_cvt_pk_bf16_f32 v31, v26, v27
	global_store_dwordx4 v142, v[28:31], s[36:37]
	ds_bpermute_b32 v214, v160, v20
	ds_bpermute_b32 v215, v160, v21
	ds_bpermute_b32 v216, v160, v22
	ds_bpermute_b32 v217, v160, v23
	ds_bpermute_b32 v218, v160, v16
	ds_bpermute_b32 v219, v160, v17
	ds_bpermute_b32 v220, v160, v18
	ds_bpermute_b32 v221, v160, v19
	s_waitcnt vmcnt(1)
	s_waitcnt lgkmcnt(0)
; __device__ __forceinline__ unsigned pkbf(float lo, float hi) { f32x2_t v = {lo, hi}; bf16x2_t b = __builtin_convertvector(v, bf16x2_t); return __builtin_bit_cast(unsigned, b); }
;     __device__ __forceinline__ void operator()(const f32x4 (&acc)[2][2][4][2], const pg8::Unit& u, int wr, int wc, int fr, int fq) const {
;     ...
;                 const int t = row & (SEQ - 1);
; #pragma unroll
;                 for (int bj = 0; bj < 2; ++bj) {
;                     f32x4 v0 = acc[ai][bj][m][0], v1 = acc[ai][bj][m][1];
;                     if (kind < 2) {
;                         v0 = v0 * rs * *(const f32x4*)(gp + 32 * bj); v1 = v1 * rs * *(const f32x4*)(gp + 32 * bj + 4);
;                         if (dorope) {
;                             const int pos = bj ? (t & 63) : (t >> 6);
;                             const f32x4 c0 = *(const f32x4*)(rp + pos * 16), c1 = *(const f32x4*)(rp + pos * 16 + 4);
;                             const f32x4 s0 = *(const f32x4*)(rp + 2048 + pos * 16), s1 = *(const f32x4*)(rp + 2048 + pos * 16 + 4);
;                             f32x4 o0, o1;
; #pragma unroll
;                             for (int i = 0; i < 4; ++i) { const float p0 = __uint_as_float((unsigned)__builtin_amdgcn_ds_bpermute(paddr, (int)__float_as_uint(v0[i]))) * s0[i], p1 = __uint_as_float((unsigned)__builtin_amdgcn_ds_bpermute(paddr, (int)__float_as_uint(v1[i]))) * s1[i];
;                                 o0[i] = v0[i] * c0[i] + (fq >= 2 ? p0 : -p0); o1[i] = v1[i] * c1[i] + (fq >= 2 ? p1 : -p1); }
;                             v0 = o0; v1 = o1;
;                         }
;                     }
;                     u32x4 w; w.x = pkbf(v0[0], v0[1]); w.y = pkbf(v0[2], v0[3]); w.z = pkbf(v1[0], v1[1]); w.w = pkbf(v1[2], v1[3]);
;                     *(u32x4*)(dst + (size_t)row * pitch + 32 * bj) = w;
;                 }
	v_mul_f32_e32 v214, v206, v214
	v_mul_f32_e32 v215, v207, v215
	v_mul_f32_e32 v216, v208, v216
	v_mul_f32_e32 v217, v209, v217
	v_cndmask_b32_e64 v214, -v214, v214, s[6:7]
	v_cndmask_b32_e64 v215, -v215, v215, s[6:7]
	v_cndmask_b32_e64 v216, -v216, v216, s[6:7]
	v_cndmask_b32_e64 v217, -v217, v217, s[6:7]
	v_fma_f32 v20, v20, v198, v214
	v_fma_f32 v21, v21, v199, v215
	v_fma_f32 v22, v22, v200, v216
	v_fma_f32 v23, v23, v201, v217
	v_mul_f32_e32 v218, v210, v218
	v_mul_f32_e32 v219, v211, v219
	v_mul_f32_e32 v220, v212, v220
	v_mul_f32_e32 v221, v213, v221
	v_cndmask_b32_e64 v218, -v218, v218, s[6:7]
	v_cndmask_b32_e64 v219, -v219, v219, s[6:7]
	v_cndmask_b32_e64 v220, -v220, v220, s[6:7]
	v_cndmask_b32_e64 v221, -v221, v221, s[6:7]
	v_fma_f32 v16, v16, v202, v218
	v_fma_f32 v17, v17, v203, v219
	v_fma_f32 v18, v18, v204, v220
	v_fma_f32 v19, v19, v205, v221
	v_cvt_pk_bf16_f32 v20, v20, v21
	v_cvt_pk_bf16_f32 v21, v22, v23
	v_cvt_pk_bf16_f32 v22, v16, v17
	v_cvt_pk_bf16_f32 v23, v18, v19
	global_store_dwordx4 v142, v[20:23], s[36:37] offset:64
	v_lshl_add_u32 v221, s12, 8, v158
	v_add_u32_e32 v221, 176, v221
	v_and_b32_e32 v218, 63, v221
	v_lshlrev_b32_e32 v218, 6, v218
	v_mov_b32_e32 v219, 0
	v_lshl_add_u64 v[214:215], v[138:139], 0, v[218:219]
	v_lshl_add_u64 v[216:217], v[140:141], 0, v[218:219]
	global_load_dwordx4 v[198:201], v[214:215], off
	global_load_dwordx4 v[202:205], v[214:215], off offset:16
	global_load_dwordx4 v[206:209], v[216:217], off
	global_load_dwordx4 v[210:213], v[216:217], off offset:16
	v_mul_f32_e32 v143, v13, v13
	v_mul_f32_e32 v144, v15, v15
	v_fmac_f32_e32 v143, v12, v12
	v_fmac_f32_e32 v144, v14, v14
	v_add_f32_e32 v142, v143, v144
	v_mul_f32_e32 v143, v9, v9
	v_mul_f32_e32 v144, v11, v11
	v_fmac_f32_e32 v143, v8, v8
	v_fmac_f32_e32 v144, v10, v10
	v_add_f32_e32 v143, v143, v144
	v_add_f32_e32 v142, v142, v143
	v_mul_f32_e32 v143, v5, v5
	v_mul_f32_e32 v144, v7, v7
	v_fmac_f32_e32 v143, v4, v4
	v_fmac_f32_e32 v144, v6, v6
	v_add_f32_e32 v143, v143, v144
	v_add_f32_e32 v142, v142, v143
	v_mul_f32_e32 v143, v1, v1
	v_mul_f32_e32 v144, v3, v3
	v_fmac_f32_e32 v143, v0, v0
	v_fmac_f32_e32 v144, v2, v2
	v_add_f32_e32 v143, v143, v144
	v_add_f32_e32 v142, v142, v143
	v_mov_b32_e32 v143, v142
	s_nop 1
	v_permlane16_swap_b32_e32 v142, v143
	v_add_f32_e32 v142, v142, v143
	v_mov_b32_e32 v143, v142
	s_nop 1
	v_permlane32_swap_b32_e32 v142, v143
	v_add_f32_e32 v142, v142, v143
	v_fmamk_f32 v144, v142, 0x3c800000, v153
	v_rsq_f32_e32 v144, v144
	s_nop 0
	v_mul_f32_e32 v12, v12, v144
	v_mul_f32_e32 v13, v13, v144
	v_mul_f32_e32 v14, v14, v144
	v_mul_f32_e32 v15, v15, v144
	v_mul_f32_e32 v12, v12, v162
	v_mul_f32_e32 v13, v13, v163
	v_mul_f32_e32 v14, v14, v164
	v_mul_f32_e32 v15, v15, v165
	v_mul_f32_e32 v8, v8, v144
	v_mul_f32_e32 v9, v9, v144
	v_mul_f32_e32 v10, v10, v144
	v_mul_f32_e32 v11, v11, v144
	v_mul_f32_e32 v8, v8, v166
	v_mul_f32_e32 v9, v9, v167
	v_mul_f32_e32 v10, v10, v168
	v_mul_f32_e32 v11, v11, v169
	v_mul_f32_e32 v4, v4, v144
	v_mul_f32_e32 v5, v5, v144
	v_mul_f32_e32 v6, v6, v144
	v_mul_f32_e32 v7, v7, v144
	v_mul_f32_e32 v4, v4, v170
	v_mul_f32_e32 v5, v5, v171
	v_mul_f32_e32 v6, v6, v172
	v_mul_f32_e32 v7, v7, v173
	v_mul_f32_e32 v0, v0, v144
	v_mul_f32_e32 v1, v1, v144
	v_mul_f32_e32 v2, v2, v144
	v_mul_f32_e32 v3, v3, v144
	v_mul_f32_e32 v0, v0, v174
	v_mul_f32_e32 v1, v1, v175
	v_mul_f32_e32 v2, v2, v176
	v_mul_f32_e32 v3, v3, v177
	ds_bpermute_b32 v214, v160, v12
	ds_bpermute_b32 v215, v160, v13
	ds_bpermute_b32 v216, v160, v14
	ds_bpermute_b32 v217, v160, v15
	ds_bpermute_b32 v218, v160, v8
	ds_bpermute_b32 v219, v160, v9
	ds_bpermute_b32 v220, v160, v10
	ds_bpermute_b32 v221, v160, v11
	s_waitcnt lgkmcnt(0)
	v_mul_f32_e32 v214, v186, v214
	v_mul_f32_e32 v215, v187, v215
	v_mul_f32_e32 v216, v188, v216
	v_mul_f32_e32 v217, v189, v217
	v_cndmask_b32_e64 v214, -v214, v214, s[6:7]
	v_cndmask_b32_e64 v215, -v215, v215, s[6:7]
	v_cndmask_b32_e64 v216, -v216, v216, s[6:7]
	v_cndmask_b32_e64 v217, -v217, v217, s[6:7]
	v_fma_f32 v12, v12, v178, v214
	v_fma_f32 v13, v13, v179, v215
	v_fma_f32 v14, v14, v180, v216
	v_fma_f32 v15, v15, v181, v217
	v_mul_f32_e32 v218, v190, v218
	v_mul_f32_e32 v219, v191, v219
	v_mul_f32_e32 v220, v192, v220
	v_mul_f32_e32 v221, v193, v221
	v_cndmask_b32_e64 v218, -v218, v218, s[6:7]
	v_cndmask_b32_e64 v219, -v219, v219, s[6:7]
	v_cndmask_b32_e64 v220, -v220, v220, s[6:7]
	v_cndmask_b32_e64 v221, -v221, v221, s[6:7]
	v_fma_f32 v8, v8, v182, v218
	v_fma_f32 v9, v9, v183, v219
	v_fma_f32 v10, v10, v184, v220
	v_fma_f32 v11, v11, v185, v221
	v_lshl_add_u32 v142, s12, 8, v158
	v_add_u32_e32 v142, 176, v142
	v_lshl_add_u32 v142, v142, s13, v154
	v_cvt_pk_bf16_f32 v12, v12, v13
	v_cvt_pk_bf16_f32 v13, v14, v15
	v_cvt_pk_bf16_f32 v14, v8, v9
	v_cvt_pk_bf16_f32 v15, v10, v11
	global_store_dwordx4 v142, v[12:15], s[36:37]
	ds_bpermute_b32 v214, v160, v4
	ds_bpermute_b32 v215, v160, v5
	ds_bpermute_b32 v216, v160, v6
	ds_bpermute_b32 v217, v160, v7
	ds_bpermute_b32 v218, v160, v0
	ds_bpermute_b32 v219, v160, v1
	ds_bpermute_b32 v220, v160, v2
	ds_bpermute_b32 v221, v160, v3
	s_waitcnt vmcnt(1)
	s_waitcnt lgkmcnt(0)
	v_mul_f32_e32 v214, v206, v214
	v_mul_f32_e32 v215, v207, v215
	v_mul_f32_e32 v216, v208, v216
	v_mul_f32_e32 v217, v209, v217
	v_cndmask_b32_e64 v214, -v214, v214, s[6:7]
	v_cndmask_b32_e64 v215, -v215, v215, s[6:7]
	v_cndmask_b32_e64 v216, -v216, v216, s[6:7]
	v_cndmask_b32_e64 v217, -v217, v217, s[6:7]
	v_fma_f32 v4, v4, v198, v214
	v_fma_f32 v5, v5, v199, v215
	v_fma_f32 v6, v6, v200, v216
	v_fma_f32 v7, v7, v201, v217
	v_mul_f32_e32 v218, v210, v218
	v_mul_f32_e32 v219, v211, v219
	v_mul_f32_e32 v220, v212, v220
	v_mul_f32_e32 v221, v213, v221
	v_cndmask_b32_e64 v218, -v218, v218, s[6:7]
	v_cndmask_b32_e64 v219, -v219, v219, s[6:7]
	v_cndmask_b32_e64 v220, -v220, v220, s[6:7]
	v_cndmask_b32_e64 v221, -v221, v221, s[6:7]
	v_fma_f32 v0, v0, v202, v218
	v_fma_f32 v1, v1, v203, v219
	v_fma_f32 v2, v2, v204, v220
	v_fma_f32 v3, v3, v205, v221
	v_cvt_pk_bf16_f32 v4, v4, v5
	v_cvt_pk_bf16_f32 v5, v6, v7
	v_cvt_pk_bf16_f32 v6, v0, v1
	v_cvt_pk_bf16_f32 v7, v2, v3
	global_store_dwordx4 v142, v[4:7], s[36:37] offset:64
	s_branch .Lqkv_join

; __device__ __forceinline__ unsigned pkbf(float lo, float hi) { f32x2_t v = {lo, hi}; bf16x2_t b = __builtin_convertvector(v, bf16x2_t); return __builtin_bit_cast(unsigned, b); }
;     __device__ __forceinline__ void operator()(const f32x4 (&acc)[2][2][4][2], const pg8::Unit& u, int wr, int wc, int fr, int fq) const {
;         const int row0 = u.pm * 256 + wr * 64 + fr, col0 = u.pn * 256 + wc * 32 + 8 * fq;
; #pragma unroll
;         for (int ai = 0; ai < 2; ++ai)
; #pragma unroll
;             for (int m = 0; m < 4; ++m) { bf16_t* rowp = O + (size_t)(row0 + ai * 128 + m * 16) * ldc + col0;
; #pragma unroll
;                 for (int bj = 0; bj < 2; ++bj) { f32x4 v0 = acc[ai][bj][m][0], v1 = acc[ai][bj][m][1];
; #pragma unroll
;                     for (int i = 0; i < 4; ++i) { float a = fmaxf(v0[i], 0.f), b = fmaxf(v1[i], 0.f); v0[i] = a * a; v1[i] = b * b; }
;                     u32x4 w; w.x = pkbf(v0[0], v0[1]); w.y = pkbf(v0[2], v0[3]); w.z = pkbf(v1[0], v1[1]); w.w = pkbf(v1[2], v1[3]);
;                     *(u32x4*)(rowp + bj * 128) = w; } }
.LBB0_806:
	v_lshl_add_u32 v140, s24, 8, v136
	v_lshl_or_b32 v134, s22, 8, v138
	v_ashrrev_i32_e32 v141, 31, v140
	v_readlane_b32 s26, v241, 37
	v_ashrrev_i32_e32 v135, 31, v134
	v_lshlrev_b64 v[142:143], 13, v[140:141]
	v_readlane_b32 s27, v241, 38
	v_lshl_add_u64 v[142:143], s[26:27], 0, v[142:143]
	v_lshlrev_b64 v[144:145], 1, v[134:135]
	v_max_f32_e32 v120, 0, v120
	v_max_f32_e32 v121, 0, v121
	v_lshl_add_u64 v[134:135], v[142:143], 0, v[144:145]
	v_mul_f32_e32 v142, v120, v120
	v_mul_f32_e32 v143, v121, v121
	v_max_f32_e32 v122, 0, v122
	v_max_f32_e32 v124, 0, v124
	v_max_f32_e32 v125, 0, v125
	v_max_f32_e32 v120, 0, v126
	v_max_f32_e32 v121, 0, v127
	v_max_f32_e32 v123, 0, v123
	v_mul_f32_e32 v124, v124, v124
	v_mul_f32_e32 v125, v125, v125
	v_mul_f32_e32 v126, v120, v120
	v_mul_f32_e32 v127, v121, v121
	v_mul_f32_e32 v146, v122, v122
	v_mul_f32_e32 v147, v123, v123
	v_cvt_pk_bf16_f32 v120, v124, v125
	v_cvt_pk_bf16_f32 v121, v126, v127
	v_cvt_pk_bf16_f32 v122, v142, v143
	v_cvt_pk_bf16_f32 v123, v146, v147
	v_max_f32_e32 v112, 0, v112
	v_max_f32_e32 v113, 0, v113
	global_store_dwordx4 v[134:135], v[120:123], off
	s_nop 1
	v_mul_f32_e32 v120, v112, v112
	v_mul_f32_e32 v121, v113, v113
	v_max_f32_e32 v114, 0, v114
	v_max_f32_e32 v116, 0, v116
	v_max_f32_e32 v117, 0, v117
	v_max_f32_e32 v112, 0, v118
	v_max_f32_e32 v113, 0, v119
	v_max_f32_e32 v115, 0, v115
	v_mul_f32_e32 v116, v116, v116
	v_mul_f32_e32 v117, v117, v117
	v_mul_f32_e32 v118, v112, v112
	v_mul_f32_e32 v119, v113, v113
	v_mul_f32_e32 v122, v114, v114
	v_mul_f32_e32 v123, v115, v115
	v_cvt_pk_bf16_f32 v112, v116, v117
	v_cvt_pk_bf16_f32 v113, v118, v119
	v_cvt_pk_bf16_f32 v114, v120, v121
	v_cvt_pk_bf16_f32 v115, v122, v123
	v_max_f32_e32 v104, 0, v104
	v_max_f32_e32 v105, 0, v105
	global_store_dwordx4 v[134:135], v[112:115], off offset:256
	s_nop 1
	v_or_b32_e32 v112, 16, v140
	v_mul_f32_e32 v114, v104, v104
	v_mul_f32_e32 v115, v105, v105
	v_ashrrev_i32_e32 v113, 31, v112
	v_max_f32_e32 v106, 0, v106
	v_lshlrev_b64 v[112:113], 13, v[112:113]
	v_max_f32_e32 v108, 0, v108
	v_max_f32_e32 v109, 0, v109
	v_max_f32_e32 v104, 0, v110
	v_max_f32_e32 v105, 0, v111
	v_max_f32_e32 v107, 0, v107
	v_lshl_add_u64 v[112:113], s[26:27], 0, v[112:113]
	v_mul_f32_e32 v108, v108, v108
	v_mul_f32_e32 v109, v109, v109
	v_mul_f32_e32 v110, v104, v104
	v_mul_f32_e32 v111, v105, v105
	v_mul_f32_e32 v116, v106, v106
	v_mul_f32_e32 v117, v107, v107
	v_lshl_add_u64 v[112:113], v[112:113], 0, v[144:145]
	v_cvt_pk_bf16_f32 v104, v108, v109
	v_cvt_pk_bf16_f32 v105, v110, v111
	v_cvt_pk_bf16_f32 v106, v114, v115
	v_cvt_pk_bf16_f32 v107, v116, v117
	v_max_f32_e32 v96, 0, v96
	v_max_f32_e32 v97, 0, v97
	global_store_dwordx4 v[112:113], v[104:107], off
	s_nop 1
	v_mul_f32_e32 v104, v96, v96
	v_mul_f32_e32 v105, v97, v97
	v_max_f32_e32 v98, 0, v98
	v_max_f32_e32 v100, 0, v100
	v_max_f32_e32 v101, 0, v101
	v_max_f32_e32 v96, 0, v102
	v_max_f32_e32 v97, 0, v103
	v_max_f32_e32 v99, 0, v99
	v_mul_f32_e32 v100, v100, v100
	v_mul_f32_e32 v101, v101, v101
	v_mul_f32_e32 v102, v96, v96
	v_mul_f32_e32 v103, v97, v97
	v_mul_f32_e32 v106, v98, v98
	v_mul_f32_e32 v107, v99, v99
	v_cvt_pk_bf16_f32 v96, v100, v101
	v_cvt_pk_bf16_f32 v97, v102, v103
	v_cvt_pk_bf16_f32 v98, v104, v105
	v_cvt_pk_bf16_f32 v99, v106, v107
	v_max_f32_e32 v88, 0, v88
	v_max_f32_e32 v89, 0, v89
	global_store_dwordx4 v[112:113], v[96:99], off offset:256
	s_nop 1
	v_or_b32_e32 v96, 32, v140
	v_mul_f32_e32 v98, v88, v88
	v_mul_f32_e32 v99, v89, v89
	v_ashrrev_i32_e32 v97, 31, v96
	v_max_f32_e32 v90, 0, v90
	v_lshlrev_b64 v[96:97], 13, v[96:97]
	v_max_f32_e32 v92, 0, v92
	v_max_f32_e32 v93, 0, v93
	v_max_f32_e32 v88, 0, v94
	v_max_f32_e32 v89, 0, v95
	v_max_f32_e32 v91, 0, v91
	v_lshl_add_u64 v[96:97], s[26:27], 0, v[96:97]
	v_mul_f32_e32 v92, v92, v92
	v_mul_f32_e32 v93, v93, v93
	v_mul_f32_e32 v94, v88, v88
	v_mul_f32_e32 v95, v89, v89
	v_mul_f32_e32 v100, v90, v90
	v_mul_f32_e32 v101, v91, v91
	v_lshl_add_u64 v[96:97], v[96:97], 0, v[144:145]
	v_cvt_pk_bf16_f32 v88, v92, v93
	v_cvt_pk_bf16_f32 v89, v94, v95
	v_cvt_pk_bf16_f32 v90, v98, v99
	v_cvt_pk_bf16_f32 v91, v100, v101
	v_max_f32_e32 v80, 0, v80
	v_max_f32_e32 v81, 0, v81
	global_store_dwordx4 v[96:97], v[88:91], off
	s_nop 1
	v_mul_f32_e32 v88, v80, v80
	v_mul_f32_e32 v89, v81, v81
	v_max_f32_e32 v82, 0, v82
	v_max_f32_e32 v84, 0, v84
	v_max_f32_e32 v85, 0, v85
	v_max_f32_e32 v80, 0, v86
	v_max_f32_e32 v81, 0, v87
	v_max_f32_e32 v83, 0, v83
	v_mul_f32_e32 v84, v84, v84
	v_mul_f32_e32 v85, v85, v85
	v_mul_f32_e32 v86, v80, v80
	v_mul_f32_e32 v87, v81, v81
	v_mul_f32_e32 v90, v82, v82
	v_mul_f32_e32 v91, v83, v83
	v_cvt_pk_bf16_f32 v80, v84, v85
	v_cvt_pk_bf16_f32 v81, v86, v87
	v_cvt_pk_bf16_f32 v82, v88, v89
	v_cvt_pk_bf16_f32 v83, v90, v91
	v_max_f32_e32 v72, 0, v72
	v_max_f32_e32 v73, 0, v73
	global_store_dwordx4 v[96:97], v[80:83], off offset:256
	s_nop 1
	v_or_b32_e32 v80, 48, v140
	v_mul_f32_e32 v82, v72, v72
	v_mul_f32_e32 v83, v73, v73
	v_ashrrev_i32_e32 v81, 31, v80
	v_max_f32_e32 v74, 0, v74
	v_lshlrev_b64 v[80:81], 13, v[80:81]
	v_max_f32_e32 v76, 0, v76
	v_max_f32_e32 v77, 0, v77
	v_max_f32_e32 v72, 0, v78
	v_max_f32_e32 v73, 0, v79
	v_max_f32_e32 v75, 0, v75
	v_lshl_add_u64 v[80:81], s[26:27], 0, v[80:81]
	v_mul_f32_e32 v76, v76, v76
	v_mul_f32_e32 v77, v77, v77
	v_mul_f32_e32 v78, v72, v72
	v_mul_f32_e32 v79, v73, v73
	v_mul_f32_e32 v84, v74, v74
	v_mul_f32_e32 v85, v75, v75
	v_lshl_add_u64 v[80:81], v[80:81], 0, v[144:145]
	v_cvt_pk_bf16_f32 v72, v76, v77
	v_cvt_pk_bf16_f32 v73, v78, v79
	v_cvt_pk_bf16_f32 v74, v82, v83
	v_cvt_pk_bf16_f32 v75, v84, v85
	v_max_f32_e32 v64, 0, v64
; __device__ __forceinline__ unsigned pkbf(float lo, float hi) { f32x2_t v = {lo, hi}; bf16x2_t b = __builtin_convertvector(v, bf16x2_t); return __builtin_bit_cast(unsigned, b); }
;     __device__ __forceinline__ void operator()(const f32x4 (&acc)[2][2][4][2], const pg8::Unit& u, int wr, int wc, int fr, int fq) const {
;         const int row0 = u.pm * 256 + wr * 64 + fr, col0 = u.pn * 256 + wc * 32 + 8 * fq;
; #pragma unroll
;         for (int ai = 0; ai < 2; ++ai)
; #pragma unroll
;             for (int m = 0; m < 4; ++m) { bf16_t* rowp = O + (size_t)(row0 + ai * 128 + m * 16) * ldc + col0;
; #pragma unroll
;                 for (int bj = 0; bj < 2; ++bj) { f32x4 v0 = acc[ai][bj][m][0], v1 = acc[ai][bj][m][1];
; #pragma unroll
;                     for (int i = 0; i < 4; ++i) { float a = fmaxf(v0[i], 0.f), b = fmaxf(v1[i], 0.f); v0[i] = a * a; v1[i] = b * b; }
;                     u32x4 w; w.x = pkbf(v0[0], v0[1]); w.y = pkbf(v0[2], v0[3]); w.z = pkbf(v1[0], v1[1]); w.w = pkbf(v1[2], v1[3]);
;                     *(u32x4*)(rowp + bj * 128) = w; } }
	v_max_f32_e32 v65, 0, v65
	global_store_dwordx4 v[80:81], v[72:75], off
	s_nop 1
	v_mul_f32_e32 v72, v64, v64
	v_mul_f32_e32 v73, v65, v65
	v_max_f32_e32 v66, 0, v66
	v_max_f32_e32 v68, 0, v68
	v_max_f32_e32 v69, 0, v69
	v_max_f32_e32 v64, 0, v70
	v_max_f32_e32 v65, 0, v71
	v_max_f32_e32 v67, 0, v67
	v_mul_f32_e32 v68, v68, v68
	v_mul_f32_e32 v69, v69, v69
	v_mul_f32_e32 v70, v64, v64
	v_mul_f32_e32 v71, v65, v65
	v_mul_f32_e32 v74, v66, v66
	v_mul_f32_e32 v75, v67, v67
	v_cvt_pk_bf16_f32 v64, v68, v69
	v_cvt_pk_bf16_f32 v65, v70, v71
	v_cvt_pk_bf16_f32 v66, v72, v73
	v_cvt_pk_bf16_f32 v67, v74, v75
	v_max_f32_e32 v56, 0, v56
	v_max_f32_e32 v57, 0, v57
	global_store_dwordx4 v[80:81], v[64:67], off offset:256
	s_nop 1
	v_mul_f32_e32 v66, v56, v56
	v_mul_f32_e32 v67, v57, v57
	v_max_f32_e32 v60, 0, v60
	v_max_f32_e32 v61, 0, v61
	v_max_f32_e32 v58, 0, v58
	v_mul_f32_e32 v60, v60, v60
	v_mul_f32_e32 v61, v61, v61
	v_max_f32_e32 v56, 0, v62
	v_max_f32_e32 v57, 0, v63
	v_max_f32_e32 v59, 0, v59
	s_mov_b32 s13, 0x100000
	v_mul_f32_e32 v62, v56, v56
	v_mul_f32_e32 v63, v57, v57
	v_mul_f32_e32 v68, v58, v58
	v_mul_f32_e32 v69, v59, v59
	v_cvt_pk_bf16_f32 v56, v60, v61
	v_add_co_u32_e32 v60, vcc, s13, v134
	v_cvt_pk_bf16_f32 v57, v62, v63
	v_cvt_pk_bf16_f32 v58, v66, v67
	v_cvt_pk_bf16_f32 v59, v68, v69
	v_addc_co_u32_e32 v61, vcc, 0, v135, vcc
	v_max_f32_e32 v48, 0, v48
	v_max_f32_e32 v49, 0, v49
	global_store_dwordx4 v[60:61], v[56:59], off
	s_nop 1
	v_mul_f32_e32 v56, v48, v48
	v_mul_f32_e32 v57, v49, v49
	v_max_f32_e32 v50, 0, v50
	v_max_f32_e32 v52, 0, v52
	v_max_f32_e32 v53, 0, v53
	v_max_f32_e32 v48, 0, v54
	v_max_f32_e32 v49, 0, v55
	v_max_f32_e32 v51, 0, v51
	v_mul_f32_e32 v52, v52, v52
	v_mul_f32_e32 v53, v53, v53
	v_mul_f32_e32 v54, v48, v48
	v_mul_f32_e32 v55, v49, v49
	v_mul_f32_e32 v58, v50, v50
	v_mul_f32_e32 v59, v51, v51
	v_lshl_add_u64 v[64:65], v[134:135], 0, s[80:81]
	v_cvt_pk_bf16_f32 v48, v52, v53
	v_cvt_pk_bf16_f32 v49, v54, v55
	v_cvt_pk_bf16_f32 v50, v56, v57
	v_cvt_pk_bf16_f32 v51, v58, v59
	v_max_f32_e32 v40, 0, v40
	v_max_f32_e32 v41, 0, v41
	global_store_dwordx4 v[64:65], v[48:51], off offset:256
	s_nop 1
	v_mul_f32_e32 v50, v40, v40
	v_mul_f32_e32 v51, v41, v41
	v_max_f32_e32 v44, 0, v44
	v_max_f32_e32 v45, 0, v45
	v_max_f32_e32 v42, 0, v42
	v_mul_f32_e32 v44, v44, v44
	v_mul_f32_e32 v45, v45, v45
	v_max_f32_e32 v40, 0, v46
	v_max_f32_e32 v41, 0, v47
	v_max_f32_e32 v43, 0, v43
	s_mov_b32 s13, 0x120000
	v_mul_f32_e32 v46, v40, v40
	v_mul_f32_e32 v47, v41, v41
	v_mul_f32_e32 v52, v42, v42
	v_mul_f32_e32 v53, v43, v43
	v_cvt_pk_bf16_f32 v40, v44, v45
	v_add_co_u32_e32 v44, vcc, s13, v134
	v_cvt_pk_bf16_f32 v41, v46, v47
	v_cvt_pk_bf16_f32 v42, v50, v51
	v_cvt_pk_bf16_f32 v43, v52, v53
	v_addc_co_u32_e32 v45, vcc, 0, v135, vcc
	v_max_f32_e32 v32, 0, v32
	v_max_f32_e32 v33, 0, v33
	global_store_dwordx4 v[44:45], v[40:43], off
	s_nop 1
	v_mul_f32_e32 v40, v32, v32
	v_mul_f32_e32 v41, v33, v33
	v_max_f32_e32 v34, 0, v34
	v_max_f32_e32 v36, 0, v36
	v_max_f32_e32 v37, 0, v37
	v_max_f32_e32 v32, 0, v38
	v_max_f32_e32 v33, 0, v39
	v_max_f32_e32 v35, 0, v35
	s_mov_b64 s[26:27], 0x120000
	v_mul_f32_e32 v36, v36, v36
	v_mul_f32_e32 v37, v37, v37
	v_mul_f32_e32 v38, v32, v32
	v_mul_f32_e32 v39, v33, v33
	v_mul_f32_e32 v42, v34, v34
	v_mul_f32_e32 v43, v35, v35
	v_lshl_add_u64 v[48:49], v[134:135], 0, s[26:27]
	v_cvt_pk_bf16_f32 v32, v36, v37
	v_cvt_pk_bf16_f32 v33, v38, v39
	v_cvt_pk_bf16_f32 v34, v40, v41
	v_cvt_pk_bf16_f32 v35, v42, v43
	v_max_f32_e32 v24, 0, v24
	v_max_f32_e32 v25, 0, v25
	global_store_dwordx4 v[48:49], v[32:35], off offset:256
	s_nop 1
	v_mul_f32_e32 v34, v24, v24
	v_mul_f32_e32 v35, v25, v25
	v_max_f32_e32 v28, 0, v28
	v_max_f32_e32 v29, 0, v29
	v_max_f32_e32 v26, 0, v26
	v_mul_f32_e32 v28, v28, v28
	v_mul_f32_e32 v29, v29, v29
	v_max_f32_e32 v24, 0, v30
	v_max_f32_e32 v25, 0, v31
	v_max_f32_e32 v27, 0, v27
	s_mov_b32 s13, 0x140000
	v_mul_f32_e32 v30, v24, v24
	v_mul_f32_e32 v31, v25, v25
	v_mul_f32_e32 v36, v26, v26
	v_mul_f32_e32 v37, v27, v27
	v_cvt_pk_bf16_f32 v24, v28, v29
	v_add_co_u32_e32 v28, vcc, s13, v134
	v_cvt_pk_bf16_f32 v25, v30, v31
	v_cvt_pk_bf16_f32 v26, v34, v35
	v_cvt_pk_bf16_f32 v27, v36, v37
	v_addc_co_u32_e32 v29, vcc, 0, v135, vcc
	v_max_f32_e32 v16, 0, v16
	v_max_f32_e32 v17, 0, v17
	global_store_dwordx4 v[28:29], v[24:27], off
	s_nop 1
	v_mul_f32_e32 v24, v16, v16
	v_mul_f32_e32 v25, v17, v17
	v_max_f32_e32 v18, 0, v18
	v_max_f32_e32 v20, 0, v20
	v_max_f32_e32 v21, 0, v21
	v_max_f32_e32 v16, 0, v22
	v_max_f32_e32 v17, 0, v23
	v_max_f32_e32 v19, 0, v19
	s_mov_b64 s[26:27], 0x140000
	v_mul_f32_e32 v20, v20, v20
	v_mul_f32_e32 v21, v21, v21
	v_mul_f32_e32 v22, v16, v16
	v_mul_f32_e32 v23, v17, v17
	v_mul_f32_e32 v26, v18, v18
	v_mul_f32_e32 v27, v19, v19
	v_lshl_add_u64 v[32:33], v[134:135], 0, s[26:27]
	v_cvt_pk_bf16_f32 v16, v20, v21
	v_cvt_pk_bf16_f32 v17, v22, v23
	v_cvt_pk_bf16_f32 v18, v24, v25
	v_cvt_pk_bf16_f32 v19, v26, v27
	v_max_f32_e32 v8, 0, v8
	v_max_f32_e32 v9, 0, v9
	global_store_dwordx4 v[32:33], v[16:19], off offset:256
	s_nop 1
	v_mul_f32_e32 v18, v8, v8
	v_mul_f32_e32 v19, v9, v9
	v_max_f32_e32 v12, 0, v12
	v_max_f32_e32 v13, 0, v13
	v_max_f32_e32 v10, 0, v10
	v_mul_f32_e32 v12, v12, v12
	v_mul_f32_e32 v13, v13, v13
	v_max_f32_e32 v8, 0, v14
	v_max_f32_e32 v9, 0, v15
	v_max_f32_e32 v11, 0, v11
	s_mov_b32 s13, 0x160000
	v_mul_f32_e32 v14, v8, v8
	v_mul_f32_e32 v15, v9, v9
	v_mul_f32_e32 v20, v10, v10
	v_mul_f32_e32 v21, v11, v11
	v_cvt_pk_bf16_f32 v8, v12, v13
	v_add_co_u32_e32 v12, vcc, s13, v134
	v_cvt_pk_bf16_f32 v9, v14, v15
	v_cvt_pk_bf16_f32 v10, v18, v19
	v_cvt_pk_bf16_f32 v11, v20, v21
	v_addc_co_u32_e32 v13, vcc, 0, v135, vcc
	v_max_f32_e32 v0, 0, v0
	v_max_f32_e32 v1, 0, v1
	global_store_dwordx4 v[12:13], v[8:11], off
	s_nop 1
	v_mul_f32_e32 v8, v0, v0
	v_mul_f32_e32 v9, v1, v1
	v_max_f32_e32 v2, 0, v2
	v_max_f32_e32 v4, 0, v4
	v_max_f32_e32 v5, 0, v5
	v_max_f32_e32 v0, 0, v6
	v_max_f32_e32 v1, 0, v7
	v_max_f32_e32 v3, 0, v3
	s_mov_b64 s[26:27], 0x160000
	v_mul_f32_e32 v4, v4, v4
	v_mul_f32_e32 v5, v5, v5
	v_mul_f32_e32 v6, v0, v0
	v_mul_f32_e32 v7, v1, v1
	v_mul_f32_e32 v10, v2, v2
	v_mul_f32_e32 v11, v3, v3
	v_lshl_add_u64 v[16:17], v[134:135], 0, s[26:27]
	v_cvt_pk_bf16_f32 v0, v4, v5
	v_cvt_pk_bf16_f32 v1, v6, v7
	v_cvt_pk_bf16_f32 v2, v8, v9
	v_cvt_pk_bf16_f32 v3, v10, v11
	s_andn2_b64 vcc, exec, s[8:9]
	s_mov_b64 s[8:9], -1
	global_store_dwordx4 v[16:17], v[0:3], off offset:256
	s_cbranch_vccnz .LBB0_795
	s_andn2_b64 vcc, exec, s[0:1]
	s_cbranch_vccnz .LBB0_794
	s_barrier
	s_branch .LBB0_794
